# GEMM hand-over: setprio before the pre-MMA barrier, redundant lgkmcnt(0) after it removed, post-MMA barrier before setprio 0
# speedup vs baseline: 1.0092x; 1.0045x over previous
; #define PG8_STAGE(bufoff, gbase, voff) do { _Pragma("unroll") for (int _i = 0; _i < 2; ++_i) \
;         __builtin_amdgcn_global_load_lds((const unsigned*)((const char*)(gbase) + (voff)[_i]), (PG8_LAS unsigned*)(lds + (bufoff) + ldsw + _i * 8192), 16, 0, 0); } while (0)
; #define PG8_LDA(dst, b, h) do { _Pragma("unroll") for (int m = 0; m < 4; ++m) _Pragma("unroll") for (int k = 0; k < 2; ++k) dst[m][k] = *(const PG8_LAS bf16x8*)(lds + PG8_SA(b, h) + aoff + m * 2048 + k * 1024); } while (0)
; #define PG8_LDB(dst, b, h) do { _Pragma("unroll") for (int n = 0; n < 2; ++n) _Pragma("unroll") for (int k = 0; k < 2; ++k) dst[n][k] = *(const PG8_LAS bf16x8*)(lds + PG8_SB(b, h) + boff + n * 2048 + k * 1024); } while (0)
; #define PG8_MMA(ai, bj, At, Bt) do { __builtin_amdgcn_s_setprio(1); _Pragma("unroll") for (int m = 0; m < 4; ++m) _Pragma("unroll") for (int n = 0; n < 2; ++n) _Pragma("unroll") for (int k = 0; k < 2; ++k) \
;         acc[ai][bj][m][n] = __builtin_amdgcn_mfma_f32_16x16x32_bf16(Bt[n][k], At[m][k], acc[ai][bj][m][n], 0, 0, 0); __builtin_amdgcn_s_setprio(0); } while (0)
; #define PG8_WAIT_V(n) asm volatile("s_waitcnt vmcnt(" #n ")" ::: "memory")
; #define PG8_WAIT_L(n) asm volatile("s_waitcnt lgkmcnt(" #n ")" ::: "memory")
; #define PG8_BAR __builtin_amdgcn_s_barrier()
; #define PG8_SCHED __builtin_amdgcn_sched_barrier(0)
; template <class Epi, class Sched, bool ALIGN_EPI = false, bool SP2 = false>
; __device__ __forceinline__ void gemm_phase(PG8_LAS unsigned char* lds, const Gemm g, const Sched& S, const Epi& E) {
;     ...
;             PG8_LDB(B0, 0, 0); PG8_LDB(B1, 0, 1); PG8_SCHED; PG8_LDA(At, 0, 0); PG8_STAGE(PG8_SA(1, 1), a1 + hstep, voffA);
;             PG8_WAIT_V(8); PG8_WAIT_L(0); PG8_BAR; PG8_MMA(0, 0, At, B0); PG8_MMA(0, 1, At, B1); PG8_BAR; PG8_SCHED;
;             PG8_LDA(At, 0, 1); PG8_STAGE(PG8_SB(0, 0), b2, voffB); PG8_STAGE(PG8_SB(0, 1), b2 + hstep, voffB); PG8_STAGE(PG8_SA(0, 0), a2, voffA);
;             PG8_WAIT_V(8); PG8_WAIT_L(0); PG8_BAR; PG8_MMA(1, 0, At, B0); PG8_MMA(1, 1, At, B1); PG8_BAR; PG8_SCHED;
.LBB0_132:
	ds_read_b128 v[152:155], v171
	ds_read_b128 v[176:179], v171 offset:1024
	ds_read_b128 v[180:183], v171 offset:2048
	ds_read_b128 v[184:187], v171 offset:3072
	ds_read_b128 v[188:191], v172
	ds_read_b128 v[192:195], v172 offset:1024
	ds_read_b128 v[198:201], v172 offset:2048
	ds_read_b128 v[202:205], v172 offset:3072
	s_add_u32 s46, s2, 0xfff00080
	s_addc_u32 s47, s3, -1
	s_cmp_eq_u32 s82, 60
	s_cselect_b32 s49, s35, s47
	s_cselect_b32 s48, s43, s46
	s_cselect_b32 s47, s17, s81
	s_cselect_b32 s46, s79, s80
	v_lshl_add_u64 v[156:157], s[2:3], 0, v[144:145]
	s_add_i32 m0, s45, 0xc000
	ds_read_b128 v[206:209], v173
	ds_read_b128 v[210:213], v173 offset:1024
	ds_read_b128 v[214:217], v173 offset:2048
	ds_read_b128 v[218:221], v173 offset:3072
	ds_read_b128 v[222:225], v173 offset:4096
	ds_read_b128 v[226:229], v173 offset:5120
	ds_read_b128 v[230:233], v173 offset:6144
	ds_read_b128 v[234:237], v173 offset:7168
	global_load_lds_dwordx4 v[156:157], off
	v_lshl_add_u64 v[156:157], s[2:3], 0, v[146:147]
	s_add_i32 m0, s45, 0xe000
	s_nop 0
	global_load_lds_dwordx4 v[156:157], off
	s_waitcnt vmcnt(8)
	s_waitcnt lgkmcnt(0)
	s_setprio 1
	s_barrier
	v_mfma_f32_16x16x32_bf16 v[126:129], v[152:155], v[206:209], v[126:129]
	v_mfma_f32_16x16x32_bf16 v[122:125], v[180:183], v[206:209], v[122:125]
	v_mfma_f32_16x16x32_bf16 v[110:113], v[152:155], v[214:217], v[110:113]
	v_mfma_f32_16x16x32_bf16 v[106:109], v[180:183], v[214:217], v[106:109]
	v_mfma_f32_16x16x32_bf16 v[94:97], v[152:155], v[222:225], v[94:97]
	v_mfma_f32_16x16x32_bf16 v[90:93], v[180:183], v[222:225], v[90:93]
	v_mfma_f32_16x16x32_bf16 v[78:81], v[152:155], v[230:233], v[78:81]
	v_mfma_f32_16x16x32_bf16 v[74:77], v[180:183], v[230:233], v[74:77]
	v_mfma_f32_16x16x32_bf16 v[126:129], v[176:179], v[210:213], v[126:129]
	v_mfma_f32_16x16x32_bf16 v[122:125], v[184:187], v[210:213], v[122:125]
	v_mfma_f32_16x16x32_bf16 v[110:113], v[176:179], v[218:221], v[110:113]
	v_mfma_f32_16x16x32_bf16 v[106:109], v[184:187], v[218:221], v[106:109]
	v_mfma_f32_16x16x32_bf16 v[94:97], v[176:179], v[226:229], v[94:97]
	v_mfma_f32_16x16x32_bf16 v[90:93], v[184:187], v[226:229], v[90:93]
	v_mfma_f32_16x16x32_bf16 v[78:81], v[176:179], v[234:237], v[78:81]
	v_mfma_f32_16x16x32_bf16 v[74:77], v[184:187], v[234:237], v[74:77]
	s_setprio 0
	s_setprio 1
	v_mfma_f32_16x16x32_bf16 v[118:121], v[188:191], v[206:209], v[118:121]
	v_mfma_f32_16x16x32_bf16 v[114:117], v[198:201], v[206:209], v[114:117]
	v_mfma_f32_16x16x32_bf16 v[102:105], v[188:191], v[214:217], v[102:105]
	v_mfma_f32_16x16x32_bf16 v[98:101], v[198:201], v[214:217], v[98:101]
	v_mfma_f32_16x16x32_bf16 v[86:89], v[188:191], v[222:225], v[86:89]
	v_mfma_f32_16x16x32_bf16 v[82:85], v[198:201], v[222:225], v[82:85]
	v_mfma_f32_16x16x32_bf16 v[70:73], v[188:191], v[230:233], v[70:73]
	v_mfma_f32_16x16x32_bf16 v[66:69], v[198:201], v[230:233], v[66:69]
	v_mfma_f32_16x16x32_bf16 v[118:121], v[192:195], v[210:213], v[118:121]
	v_mfma_f32_16x16x32_bf16 v[114:117], v[202:205], v[210:213], v[114:117]
	v_mfma_f32_16x16x32_bf16 v[102:105], v[192:195], v[218:221], v[102:105]
	v_mfma_f32_16x16x32_bf16 v[98:101], v[202:205], v[218:221], v[98:101]
	v_mfma_f32_16x16x32_bf16 v[86:89], v[192:195], v[226:229], v[86:89]
	v_mfma_f32_16x16x32_bf16 v[82:85], v[202:205], v[226:229], v[82:85]
	v_mfma_f32_16x16x32_bf16 v[70:73], v[192:195], v[234:237], v[70:73]
	v_mfma_f32_16x16x32_bf16 v[66:69], v[202:205], v[234:237], v[66:69]
	s_barrier
	s_setprio 0
	s_add_i32 s83, s74, s55
	v_lshl_add_u64 v[156:157], s[46:47], 0, v[132:133]
	s_mov_b32 m0, s83
	ds_read_b128 v[206:209], v173 offset:16384
	ds_read_b128 v[210:213], v173 offset:17408
	ds_read_b128 v[214:217], v173 offset:18432
	ds_read_b128 v[218:221], v173 offset:19456
	ds_read_b128 v[222:225], v173 offset:20480
	ds_read_b128 v[226:229], v173 offset:21504
	ds_read_b128 v[230:233], v173 offset:22528
	ds_read_b128 v[234:237], v173 offset:23552
	global_load_lds_dwordx4 v[156:157], off
	s_add_i32 m0, s83, 0x2000
	s_add_u32 s84, s46, 0x100000
	v_lshl_add_u64 v[238:239], s[46:47], 0, v[136:137]
	s_addc_u32 s85, s47, 0
	s_add_i32 s83, s75, s55
	global_load_lds_dwordx4 v[238:239], off
	v_lshl_add_u64 v[240:241], s[84:85], 0, v[132:133]
	s_mov_b32 m0, s83
	v_lshl_add_u64 v[242:243], s[48:49], 0, v[134:135]
	global_load_lds_dwordx4 v[240:241], off
	v_lshl_add_u64 v[240:241], s[84:85], 0, v[136:137]
	s_add_i32 m0, s83, 0x2000
	s_nop 0
	global_load_lds_dwordx4 v[240:241], off
	v_lshl_add_u64 v[240:241], s[48:49], 0, v[130:131]
	s_mov_b32 m0, s45
	s_nop 0
	global_load_lds_dwordx4 v[240:241], off
	s_mov_b32 m0, s56
	s_nop 0
	global_load_lds_dwordx4 v[242:243], off
	s_waitcnt vmcnt(8)
	s_waitcnt lgkmcnt(0)
	s_setprio 1
	s_barrier
; #define PG8_STAGE(bufoff, gbase, voff) do { _Pragma("unroll") for (int _i = 0; _i < 2; ++_i) \
;         __builtin_amdgcn_global_load_lds((const unsigned*)((const char*)(gbase) + (voff)[_i]), (PG8_LAS unsigned*)(lds + (bufoff) + ldsw + _i * 8192), 16, 0, 0); } while (0)
; #define PG8_LDA(dst, b, h) do { _Pragma("unroll") for (int m = 0; m < 4; ++m) _Pragma("unroll") for (int k = 0; k < 2; ++k) dst[m][k] = *(const PG8_LAS bf16x8*)(lds + PG8_SA(b, h) + aoff + m * 2048 + k * 1024); } while (0)
; #define PG8_LDB(dst, b, h) do { _Pragma("unroll") for (int n = 0; n < 2; ++n) _Pragma("unroll") for (int k = 0; k < 2; ++k) dst[n][k] = *(const PG8_LAS bf16x8*)(lds + PG8_SB(b, h) + boff + n * 2048 + k * 1024); } while (0)
; #define PG8_MMA(ai, bj, At, Bt) do { __builtin_amdgcn_s_setprio(1); _Pragma("unroll") for (int m = 0; m < 4; ++m) _Pragma("unroll") for (int n = 0; n < 2; ++n) _Pragma("unroll") for (int k = 0; k < 2; ++k) \
;         acc[ai][bj][m][n] = __builtin_amdgcn_mfma_f32_16x16x32_bf16(Bt[n][k], At[m][k], acc[ai][bj][m][n], 0, 0, 0); __builtin_amdgcn_s_setprio(0); } while (0)
; #define PG8_WAIT_V(n) asm volatile("s_waitcnt vmcnt(" #n ")" ::: "memory")
; #define PG8_WAIT_L(n) asm volatile("s_waitcnt lgkmcnt(" #n ")" ::: "memory")
; #define PG8_BAR __builtin_amdgcn_s_barrier()
; #define PG8_SCHED __builtin_amdgcn_sched_barrier(0)
; template <class Epi, class Sched, bool ALIGN_EPI = false, bool SP2 = false>
; __device__ __forceinline__ void gemm_phase(PG8_LAS unsigned char* lds, const Gemm g, const Sched& S, const Epi& E) {
;     ...
;             PG8_WAIT_V(8); PG8_WAIT_L(0); PG8_BAR; PG8_MMA(1, 0, At, B0); PG8_MMA(1, 1, At, B1); PG8_BAR; PG8_SCHED;
;             PG8_LDB(B0, 1, 0); PG8_LDB(B1, 1, 1); PG8_SCHED; PG8_LDA(At, 1, 0); PG8_STAGE(PG8_SA(0, 1), a2 + hstep, voffA);
;             PG8_WAIT_V(8); PG8_WAIT_L(0); PG8_BAR; PG8_MMA(0, 0, At, B0); PG8_MMA(0, 1, At, B1); PG8_BAR; PG8_SCHED;
	v_mfma_f32_16x16x32_bf16 v[62:65], v[152:155], v[206:209], v[62:65]
	v_mfma_f32_16x16x32_bf16 v[58:61], v[180:183], v[206:209], v[58:61]
	v_mfma_f32_16x16x32_bf16 v[46:49], v[152:155], v[214:217], v[46:49]
	v_mfma_f32_16x16x32_bf16 v[42:45], v[180:183], v[214:217], v[42:45]
	v_mfma_f32_16x16x32_bf16 v[30:33], v[152:155], v[222:225], v[30:33]
	v_mfma_f32_16x16x32_bf16 v[26:29], v[180:183], v[222:225], v[26:29]
	v_mfma_f32_16x16x32_bf16 v[14:17], v[152:155], v[230:233], v[14:17]
	v_mfma_f32_16x16x32_bf16 v[10:13], v[180:183], v[230:233], v[10:13]
	v_mfma_f32_16x16x32_bf16 v[62:65], v[176:179], v[210:213], v[62:65]
	v_mfma_f32_16x16x32_bf16 v[58:61], v[184:187], v[210:213], v[58:61]
	v_mfma_f32_16x16x32_bf16 v[46:49], v[176:179], v[218:221], v[46:49]
	v_mfma_f32_16x16x32_bf16 v[42:45], v[184:187], v[218:221], v[42:45]
	v_mfma_f32_16x16x32_bf16 v[30:33], v[176:179], v[226:229], v[30:33]
	v_mfma_f32_16x16x32_bf16 v[26:29], v[184:187], v[226:229], v[26:29]
	v_mfma_f32_16x16x32_bf16 v[14:17], v[176:179], v[234:237], v[14:17]
	v_mfma_f32_16x16x32_bf16 v[10:13], v[184:187], v[234:237], v[10:13]
	s_setprio 0
	s_setprio 1
	v_mfma_f32_16x16x32_bf16 v[54:57], v[188:191], v[206:209], v[54:57]
	v_mfma_f32_16x16x32_bf16 v[50:53], v[198:201], v[206:209], v[50:53]
	v_mfma_f32_16x16x32_bf16 v[38:41], v[188:191], v[214:217], v[38:41]
	v_mfma_f32_16x16x32_bf16 v[34:37], v[198:201], v[214:217], v[34:37]
	v_mfma_f32_16x16x32_bf16 v[22:25], v[188:191], v[222:225], v[22:25]
	v_mfma_f32_16x16x32_bf16 v[18:21], v[198:201], v[222:225], v[18:21]
	v_mfma_f32_16x16x32_bf16 v[6:9], v[188:191], v[230:233], v[6:9]
	v_mfma_f32_16x16x32_bf16 v[2:5], v[198:201], v[230:233], v[2:5]
	v_mfma_f32_16x16x32_bf16 v[54:57], v[192:195], v[210:213], v[54:57]
	v_mfma_f32_16x16x32_bf16 v[50:53], v[202:205], v[210:213], v[50:53]
	v_mfma_f32_16x16x32_bf16 v[38:41], v[192:195], v[218:221], v[38:41]
	v_mfma_f32_16x16x32_bf16 v[34:37], v[202:205], v[218:221], v[34:37]
	v_mfma_f32_16x16x32_bf16 v[22:25], v[192:195], v[226:229], v[22:25]
	v_mfma_f32_16x16x32_bf16 v[18:21], v[202:205], v[226:229], v[18:21]
	v_mfma_f32_16x16x32_bf16 v[6:9], v[192:195], v[234:237], v[6:9]
	v_mfma_f32_16x16x32_bf16 v[2:5], v[202:205], v[234:237], v[2:5]
	s_barrier
	s_setprio 0
	s_add_i32 s83, 0, 0x18000
	v_add_u32_e32 v149, s83, v167
	s_add_i32 s84, 0, 0x1c000
	ds_read_b128 v[152:155], v149
	ds_read_b128 v[176:179], v149 offset:1024
	ds_read_b128 v[180:183], v149 offset:2048
	ds_read_b128 v[184:187], v149 offset:3072
	v_add_u32_e32 v149, s84, v167
	ds_read_b128 v[188:191], v149
	ds_read_b128 v[192:195], v149 offset:1024
	ds_read_b128 v[198:201], v149 offset:2048
	ds_read_b128 v[202:205], v149 offset:3072
	s_add_u32 s48, s48, 0x100000
	s_addc_u32 s49, s49, 0
	s_mov_b32 m0, s57
	v_lshl_add_u64 v[244:245], s[48:49], 0, v[130:131]
	ds_read_b128 v[206:209], v173 offset:32768
	ds_read_b128 v[210:213], v173 offset:33792
	ds_read_b128 v[214:217], v173 offset:34816
	ds_read_b128 v[218:221], v173 offset:35840
	ds_read_b128 v[222:225], v173 offset:36864
	ds_read_b128 v[226:229], v173 offset:37888
	ds_read_b128 v[230:233], v173 offset:38912
	ds_read_b128 v[234:237], v173 offset:39936
	global_load_lds_dwordx4 v[244:245], off
	v_lshl_add_u64 v[244:245], s[48:49], 0, v[134:135]
	s_mov_b32 m0, s58
	s_nop 0
	global_load_lds_dwordx4 v[244:245], off
	s_waitcnt vmcnt(8)
	s_waitcnt lgkmcnt(0)
	s_setprio 1
	s_barrier
	v_mfma_f32_16x16x32_bf16 v[126:129], v[152:155], v[206:209], v[126:129]
	v_mfma_f32_16x16x32_bf16 v[122:125], v[180:183], v[206:209], v[122:125]
	v_mfma_f32_16x16x32_bf16 v[110:113], v[152:155], v[214:217], v[110:113]
	v_mfma_f32_16x16x32_bf16 v[106:109], v[180:183], v[214:217], v[106:109]
	v_mfma_f32_16x16x32_bf16 v[94:97], v[152:155], v[222:225], v[94:97]
	v_mfma_f32_16x16x32_bf16 v[90:93], v[180:183], v[222:225], v[90:93]
	v_mfma_f32_16x16x32_bf16 v[78:81], v[152:155], v[230:233], v[78:81]
	v_mfma_f32_16x16x32_bf16 v[74:77], v[180:183], v[230:233], v[74:77]
	v_mfma_f32_16x16x32_bf16 v[126:129], v[176:179], v[210:213], v[126:129]
	v_mfma_f32_16x16x32_bf16 v[122:125], v[184:187], v[210:213], v[122:125]
	v_mfma_f32_16x16x32_bf16 v[110:113], v[176:179], v[218:221], v[110:113]
	v_mfma_f32_16x16x32_bf16 v[106:109], v[184:187], v[218:221], v[106:109]
	v_mfma_f32_16x16x32_bf16 v[94:97], v[176:179], v[226:229], v[94:97]
	v_mfma_f32_16x16x32_bf16 v[90:93], v[184:187], v[226:229], v[90:93]
	v_mfma_f32_16x16x32_bf16 v[78:81], v[176:179], v[234:237], v[78:81]
	v_mfma_f32_16x16x32_bf16 v[74:77], v[184:187], v[234:237], v[74:77]
	s_setprio 0
	s_setprio 1
	v_mfma_f32_16x16x32_bf16 v[118:121], v[188:191], v[206:209], v[118:121]
	v_mfma_f32_16x16x32_bf16 v[114:117], v[198:201], v[206:209], v[114:117]
	v_mfma_f32_16x16x32_bf16 v[102:105], v[188:191], v[214:217], v[102:105]
	v_mfma_f32_16x16x32_bf16 v[98:101], v[198:201], v[214:217], v[98:101]
	v_mfma_f32_16x16x32_bf16 v[86:89], v[188:191], v[222:225], v[86:89]
	v_mfma_f32_16x16x32_bf16 v[82:85], v[198:201], v[222:225], v[82:85]
	v_mfma_f32_16x16x32_bf16 v[70:73], v[188:191], v[230:233], v[70:73]
	v_mfma_f32_16x16x32_bf16 v[66:69], v[198:201], v[230:233], v[66:69]
	v_mfma_f32_16x16x32_bf16 v[118:121], v[192:195], v[210:213], v[118:121]
	v_mfma_f32_16x16x32_bf16 v[114:117], v[202:205], v[210:213], v[114:117]
	v_mfma_f32_16x16x32_bf16 v[102:105], v[192:195], v[218:221], v[102:105]
	v_mfma_f32_16x16x32_bf16 v[98:101], v[202:205], v[218:221], v[98:101]
	v_mfma_f32_16x16x32_bf16 v[86:89], v[192:195], v[226:229], v[86:89]
	v_mfma_f32_16x16x32_bf16 v[82:85], v[202:205], v[226:229], v[82:85]
	v_mfma_f32_16x16x32_bf16 v[70:73], v[192:195], v[234:237], v[70:73]
	v_mfma_f32_16x16x32_bf16 v[66:69], v[202:205], v[234:237], v[66:69]
	s_barrier
; #define PG8_STAGE(bufoff, gbase, voff) do { _Pragma("unroll") for (int _i = 0; _i < 2; ++_i) \
;         __builtin_amdgcn_global_load_lds((const unsigned*)((const char*)(gbase) + (voff)[_i]), (PG8_LAS unsigned*)(lds + (bufoff) + ldsw + _i * 8192), 16, 0, 0); } while (0)
; #define PG8_LDA(dst, b, h) do { _Pragma("unroll") for (int m = 0; m < 4; ++m) _Pragma("unroll") for (int k = 0; k < 2; ++k) dst[m][k] = *(const PG8_LAS bf16x8*)(lds + PG8_SA(b, h) + aoff + m * 2048 + k * 1024); } while (0)
; #define PG8_MMA(ai, bj, At, Bt) do { __builtin_amdgcn_s_setprio(1); _Pragma("unroll") for (int m = 0; m < 4; ++m) _Pragma("unroll") for (int n = 0; n < 2; ++n) _Pragma("unroll") for (int k = 0; k < 2; ++k) \
;         acc[ai][bj][m][n] = __builtin_amdgcn_mfma_f32_16x16x32_bf16(Bt[n][k], At[m][k], acc[ai][bj][m][n], 0, 0, 0); __builtin_amdgcn_s_setprio(0); } while (0)
; #define PG8_WAIT_V(n) asm volatile("s_waitcnt vmcnt(" #n ")" ::: "memory")
; #define PG8_WAIT_L(n) asm volatile("s_waitcnt lgkmcnt(" #n ")" ::: "memory")
; #define PG8_BAR __builtin_amdgcn_s_barrier()
; #define PG8_SCHED __builtin_amdgcn_sched_barrier(0)
; template <class Epi, class Sched, bool ALIGN_EPI = false, bool SP2 = false>
; __device__ __forceinline__ void gemm_phase(PG8_LAS unsigned char* lds, const Gemm g, const Sched& S, const Epi& E) {
;     ...
;             PG8_LDA(At, 1, 1); PG8_STAGE(PG8_SB(1, 0), b3, voffB); PG8_STAGE(PG8_SB(1, 1), b3 + hstep, voffB); PG8_STAGE(PG8_SA(1, 0), a3, voffA);
;             PG8_WAIT_V(8); PG8_WAIT_L(0); PG8_BAR; PG8_MMA(1, 0, At, B0); PG8_MMA(1, 1, At, B1); PG8_BAR; PG8_SCHED;
;     ...
;         if constexpr (ALIGN_EPI) { if (wr == 0) PG8_BAR; }
	s_setprio 0
	s_add_i32 s48, s83, s55
	v_lshl_add_u64 v[156:157], v[156:157], 0, s[10:11]
	s_mov_b32 m0, s48
	ds_read_b128 v[206:209], v173 offset:49152
	ds_read_b128 v[210:213], v173 offset:50176
	ds_read_b128 v[214:217], v173 offset:51200
	ds_read_b128 v[218:221], v173 offset:52224
	ds_read_b128 v[222:225], v173 offset:53248
	ds_read_b128 v[226:229], v173 offset:54272
	ds_read_b128 v[230:233], v173 offset:55296
	ds_read_b128 v[234:237], v173 offset:56320
	global_load_lds_dwordx4 v[156:157], off
	s_add_i32 m0, s48, 0x2000
	s_add_u32 s46, s46, 0x100080
	v_lshl_add_u64 v[156:157], v[238:239], 0, s[10:11]
	s_addc_u32 s47, s47, 0
	s_add_i32 s48, s84, s55
	global_load_lds_dwordx4 v[156:157], off
	v_lshl_add_u64 v[156:157], s[46:47], 0, v[132:133]
	s_mov_b32 m0, s48
	s_nop 0
	global_load_lds_dwordx4 v[156:157], off
	v_lshl_add_u64 v[156:157], s[46:47], 0, v[136:137]
	s_add_i32 m0, s48, 0x2000
	s_nop 0
	global_load_lds_dwordx4 v[156:157], off
	v_lshl_add_u64 v[156:157], v[240:241], 0, s[10:11]
	s_mov_b32 m0, s63
	s_nop 0
	global_load_lds_dwordx4 v[156:157], off
	v_lshl_add_u64 v[156:157], v[242:243], 0, s[10:11]
	s_mov_b32 m0, s70
	s_nop 0
	global_load_lds_dwordx4 v[156:157], off
	s_waitcnt vmcnt(8)
	s_waitcnt lgkmcnt(0)
	s_setprio 1
	s_barrier
	v_mfma_f32_16x16x32_bf16 v[62:65], v[152:155], v[206:209], v[62:65]
	v_mfma_f32_16x16x32_bf16 v[58:61], v[180:183], v[206:209], v[58:61]
	v_mfma_f32_16x16x32_bf16 v[46:49], v[152:155], v[214:217], v[46:49]
	v_mfma_f32_16x16x32_bf16 v[42:45], v[180:183], v[214:217], v[42:45]
	v_mfma_f32_16x16x32_bf16 v[30:33], v[152:155], v[222:225], v[30:33]
	v_mfma_f32_16x16x32_bf16 v[26:29], v[180:183], v[222:225], v[26:29]
	v_mfma_f32_16x16x32_bf16 v[14:17], v[152:155], v[230:233], v[14:17]
	v_mfma_f32_16x16x32_bf16 v[10:13], v[180:183], v[230:233], v[10:13]
	v_mfma_f32_16x16x32_bf16 v[62:65], v[176:179], v[210:213], v[62:65]
	v_mfma_f32_16x16x32_bf16 v[58:61], v[184:187], v[210:213], v[58:61]
	v_mfma_f32_16x16x32_bf16 v[46:49], v[176:179], v[218:221], v[46:49]
	v_mfma_f32_16x16x32_bf16 v[42:45], v[184:187], v[218:221], v[42:45]
	v_mfma_f32_16x16x32_bf16 v[30:33], v[176:179], v[226:229], v[30:33]
	v_mfma_f32_16x16x32_bf16 v[26:29], v[184:187], v[226:229], v[26:29]
	v_mfma_f32_16x16x32_bf16 v[14:17], v[176:179], v[234:237], v[14:17]
	v_mfma_f32_16x16x32_bf16 v[10:13], v[184:187], v[234:237], v[10:13]
	s_setprio 0
	s_setprio 1
	v_mfma_f32_16x16x32_bf16 v[54:57], v[188:191], v[206:209], v[54:57]
	v_mfma_f32_16x16x32_bf16 v[50:53], v[198:201], v[206:209], v[50:53]
	v_mfma_f32_16x16x32_bf16 v[38:41], v[188:191], v[214:217], v[38:41]
	v_mfma_f32_16x16x32_bf16 v[34:37], v[198:201], v[214:217], v[34:37]
	v_mfma_f32_16x16x32_bf16 v[22:25], v[188:191], v[222:225], v[22:25]
	v_mfma_f32_16x16x32_bf16 v[18:21], v[198:201], v[222:225], v[18:21]
	v_mfma_f32_16x16x32_bf16 v[6:9], v[188:191], v[230:233], v[6:9]
	v_mfma_f32_16x16x32_bf16 v[2:5], v[198:201], v[230:233], v[2:5]
	v_mfma_f32_16x16x32_bf16 v[54:57], v[192:195], v[210:213], v[54:57]
	v_mfma_f32_16x16x32_bf16 v[50:53], v[202:205], v[210:213], v[50:53]
	v_mfma_f32_16x16x32_bf16 v[38:41], v[192:195], v[218:221], v[38:41]
	v_mfma_f32_16x16x32_bf16 v[34:37], v[202:205], v[218:221], v[34:37]
	v_mfma_f32_16x16x32_bf16 v[22:25], v[192:195], v[226:229], v[22:25]
	v_mfma_f32_16x16x32_bf16 v[18:21], v[202:205], v[226:229], v[18:21]
	v_mfma_f32_16x16x32_bf16 v[6:9], v[192:195], v[234:237], v[6:9]
	v_mfma_f32_16x16x32_bf16 v[2:5], v[202:205], v[234:237], v[2:5]
	s_barrier
	s_setprio 0
	s_add_i32 s82, s82, 2
	s_add_u32 s2, s2, 0x100
	s_addc_u32 s3, s3, 0
	s_add_u32 s80, s80, 0x100
	s_addc_u32 s81, s81, 0
	s_cmp_gt_u32 s82, 61
	s_cbranch_scc0 .LBB0_132
	s_and_b64 vcc, exec, s[12:13]
	s_cbranch_vccz .LBB0_135
	s_barrier

; #define PG8_STAGE(bufoff, gbase, voff) do { _Pragma("unroll") for (int _i = 0; _i < 2; ++_i) \
;         __builtin_amdgcn_global_load_lds((const unsigned*)((const char*)(gbase) + (voff)[_i]), (PG8_LAS unsigned*)(lds + (bufoff) + ldsw + _i * 8192), 16, 0, 0); } while (0)
; #define PG8_LDA(dst, b, h) do { _Pragma("unroll") for (int m = 0; m < 4; ++m) _Pragma("unroll") for (int k = 0; k < 2; ++k) dst[m][k] = *(const PG8_LAS bf16x8*)(lds + PG8_SA(b, h) + aoff + m * 2048 + k * 1024); } while (0)
; #define PG8_LDB(dst, b, h) do { _Pragma("unroll") for (int n = 0; n < 2; ++n) _Pragma("unroll") for (int k = 0; k < 2; ++k) dst[n][k] = *(const PG8_LAS bf16x8*)(lds + PG8_SB(b, h) + boff + n * 2048 + k * 1024); } while (0)
; #define PG8_MMA(ai, bj, At, Bt) do { __builtin_amdgcn_s_setprio(1); _Pragma("unroll") for (int m = 0; m < 4; ++m) _Pragma("unroll") for (int n = 0; n < 2; ++n) _Pragma("unroll") for (int k = 0; k < 2; ++k) \
;         acc[ai][bj][m][n] = __builtin_amdgcn_mfma_f32_16x16x32_bf16(Bt[n][k], At[m][k], acc[ai][bj][m][n], 0, 0, 0); __builtin_amdgcn_s_setprio(0); } while (0)
; #define PG8_WAIT_V(n) asm volatile("s_waitcnt vmcnt(" #n ")" ::: "memory")
; #define PG8_WAIT_L(n) asm volatile("s_waitcnt lgkmcnt(" #n ")" ::: "memory")
; #define PG8_BAR __builtin_amdgcn_s_barrier()
; #define PG8_SCHED __builtin_amdgcn_sched_barrier(0)
; template <class Epi, class Sched, bool ALIGN_EPI = false, bool SP2 = false>
; __device__ __forceinline__ void gemm_phase(PG8_LAS unsigned char* lds, const Gemm g, const Sched& S, const Epi& E) {
;     ...
;             PG8_LDB(B0, 0, 0); PG8_LDB(B1, 0, 1); PG8_SCHED; PG8_LDA(At, 0, 0); PG8_STAGE(PG8_SA(1, 1), a1 + hstep, voffA);
;             PG8_WAIT_V(8); PG8_WAIT_L(0); PG8_BAR; PG8_MMA(0, 0, At, B0); PG8_MMA(0, 1, At, B1); PG8_BAR; PG8_SCHED;
;             PG8_LDA(At, 0, 1); PG8_STAGE(PG8_SB(0, 0), b2, voffB); PG8_STAGE(PG8_SB(0, 1), b2 + hstep, voffB); PG8_STAGE(PG8_SA(0, 0), a2, voffA);
;             PG8_WAIT_V(8); PG8_WAIT_L(0); PG8_BAR; PG8_MMA(1, 0, At, B0); PG8_MMA(1, 1, At, B1); PG8_BAR; PG8_SCHED;
.LBB0_217:
	ds_read_b128 v[152:155], v159
	ds_read_b128 v[168:171], v159 offset:1024
	ds_read_b128 v[172:175], v159 offset:2048
	ds_read_b128 v[176:179], v159 offset:3072
	ds_read_b128 v[180:183], v160
	ds_read_b128 v[184:187], v160 offset:1024
	ds_read_b128 v[188:191], v160 offset:2048
	ds_read_b128 v[192:195], v160 offset:3072
	s_add_u32 s46, s44, 0xfff00080
	s_addc_u32 s47, s45, -1
	s_cmp_eq_u32 s80, 60
	s_cselect_b32 s49, s3, s47
	s_cselect_b32 s48, s35, s46
	s_cselect_b32 s47, s17, s79
	s_cselect_b32 s46, s43, s78
	v_lshl_add_u64 v[156:157], s[44:45], 0, v[144:145]
	s_add_i32 m0, s56, 0xc000
	ds_read_b128 v[198:201], v161
	ds_read_b128 v[202:205], v161 offset:1024
	ds_read_b128 v[206:209], v161 offset:2048
	ds_read_b128 v[210:213], v161 offset:3072
	ds_read_b128 v[214:217], v161 offset:4096
	ds_read_b128 v[218:221], v161 offset:5120
	ds_read_b128 v[222:225], v161 offset:6144
	ds_read_b128 v[226:229], v161 offset:7168
	global_load_lds_dwordx4 v[156:157], off
	v_lshl_add_u64 v[156:157], s[44:45], 0, v[146:147]
	s_add_i32 m0, s56, 0xe000
	s_nop 0
	global_load_lds_dwordx4 v[156:157], off
	s_waitcnt vmcnt(8)
	s_waitcnt lgkmcnt(0)
	s_setprio 1
	s_barrier
	v_mfma_f32_16x16x32_bf16 v[126:129], v[152:155], v[198:201], v[126:129]
	v_mfma_f32_16x16x32_bf16 v[122:125], v[172:175], v[198:201], v[122:125]
	v_mfma_f32_16x16x32_bf16 v[110:113], v[152:155], v[206:209], v[110:113]
	v_mfma_f32_16x16x32_bf16 v[106:109], v[172:175], v[206:209], v[106:109]
	v_mfma_f32_16x16x32_bf16 v[94:97], v[152:155], v[214:217], v[94:97]
	v_mfma_f32_16x16x32_bf16 v[90:93], v[172:175], v[214:217], v[90:93]
	v_mfma_f32_16x16x32_bf16 v[78:81], v[152:155], v[222:225], v[78:81]
	v_mfma_f32_16x16x32_bf16 v[74:77], v[172:175], v[222:225], v[74:77]
	v_mfma_f32_16x16x32_bf16 v[126:129], v[168:171], v[202:205], v[126:129]
	v_mfma_f32_16x16x32_bf16 v[122:125], v[176:179], v[202:205], v[122:125]
	v_mfma_f32_16x16x32_bf16 v[110:113], v[168:171], v[210:213], v[110:113]
	v_mfma_f32_16x16x32_bf16 v[106:109], v[176:179], v[210:213], v[106:109]
	v_mfma_f32_16x16x32_bf16 v[94:97], v[168:171], v[218:221], v[94:97]
	v_mfma_f32_16x16x32_bf16 v[90:93], v[176:179], v[218:221], v[90:93]
	v_mfma_f32_16x16x32_bf16 v[78:81], v[168:171], v[226:229], v[78:81]
	v_mfma_f32_16x16x32_bf16 v[74:77], v[176:179], v[226:229], v[74:77]
	s_setprio 0
	s_setprio 1
	v_mfma_f32_16x16x32_bf16 v[118:121], v[180:183], v[198:201], v[118:121]
	v_mfma_f32_16x16x32_bf16 v[114:117], v[188:191], v[198:201], v[114:117]
	v_mfma_f32_16x16x32_bf16 v[102:105], v[180:183], v[206:209], v[102:105]
	v_mfma_f32_16x16x32_bf16 v[98:101], v[188:191], v[206:209], v[98:101]
	v_mfma_f32_16x16x32_bf16 v[86:89], v[180:183], v[214:217], v[86:89]
	v_mfma_f32_16x16x32_bf16 v[82:85], v[188:191], v[214:217], v[82:85]
	v_mfma_f32_16x16x32_bf16 v[70:73], v[180:183], v[222:225], v[70:73]
	v_mfma_f32_16x16x32_bf16 v[66:69], v[188:191], v[222:225], v[66:69]
	v_mfma_f32_16x16x32_bf16 v[118:121], v[184:187], v[202:205], v[118:121]
	v_mfma_f32_16x16x32_bf16 v[114:117], v[192:195], v[202:205], v[114:117]
	v_mfma_f32_16x16x32_bf16 v[102:105], v[184:187], v[210:213], v[102:105]
	v_mfma_f32_16x16x32_bf16 v[98:101], v[192:195], v[210:213], v[98:101]
	v_mfma_f32_16x16x32_bf16 v[86:89], v[184:187], v[218:221], v[86:89]
	v_mfma_f32_16x16x32_bf16 v[82:85], v[192:195], v[218:221], v[82:85]
	v_mfma_f32_16x16x32_bf16 v[70:73], v[184:187], v[226:229], v[70:73]
	v_mfma_f32_16x16x32_bf16 v[66:69], v[192:195], v[226:229], v[66:69]
	s_barrier
	s_setprio 0
	s_add_i32 s81, s73, s55
	v_lshl_add_u64 v[156:157], s[46:47], 0, v[132:133]
	s_mov_b32 m0, s81
	ds_read_b128 v[198:201], v161 offset:16384
	ds_read_b128 v[202:205], v161 offset:17408
	ds_read_b128 v[206:209], v161 offset:18432
	ds_read_b128 v[210:213], v161 offset:19456
	ds_read_b128 v[214:217], v161 offset:20480
	ds_read_b128 v[218:221], v161 offset:21504
	ds_read_b128 v[222:225], v161 offset:22528
	ds_read_b128 v[226:229], v161 offset:23552
	global_load_lds_dwordx4 v[156:157], off
	s_add_i32 m0, s81, 0x2000
	s_add_u32 s82, s46, 0x100000
	v_lshl_add_u64 v[230:231], s[46:47], 0, v[136:137]
	s_addc_u32 s83, s47, 0
	s_add_i32 s81, s74, s55
	global_load_lds_dwordx4 v[230:231], off
	v_lshl_add_u64 v[232:233], s[82:83], 0, v[132:133]
	s_mov_b32 m0, s81
	v_lshl_add_u64 v[234:235], s[48:49], 0, v[134:135]
	global_load_lds_dwordx4 v[232:233], off
	v_lshl_add_u64 v[232:233], s[82:83], 0, v[136:137]
	s_add_i32 m0, s81, 0x2000
	s_nop 0
	global_load_lds_dwordx4 v[232:233], off
	v_lshl_add_u64 v[232:233], s[48:49], 0, v[130:131]
	s_mov_b32 m0, s56
	s_nop 0
	global_load_lds_dwordx4 v[232:233], off
	s_mov_b32 m0, s57
	s_nop 0
	global_load_lds_dwordx4 v[234:235], off
	s_waitcnt vmcnt(8)
	s_waitcnt lgkmcnt(0)
	s_setprio 1
	s_barrier
; #define PG8_STAGE(bufoff, gbase, voff) do { _Pragma("unroll") for (int _i = 0; _i < 2; ++_i) \
;         __builtin_amdgcn_global_load_lds((const unsigned*)((const char*)(gbase) + (voff)[_i]), (PG8_LAS unsigned*)(lds + (bufoff) + ldsw + _i * 8192), 16, 0, 0); } while (0)
; #define PG8_LDA(dst, b, h) do { _Pragma("unroll") for (int m = 0; m < 4; ++m) _Pragma("unroll") for (int k = 0; k < 2; ++k) dst[m][k] = *(const PG8_LAS bf16x8*)(lds + PG8_SA(b, h) + aoff + m * 2048 + k * 1024); } while (0)
; #define PG8_LDB(dst, b, h) do { _Pragma("unroll") for (int n = 0; n < 2; ++n) _Pragma("unroll") for (int k = 0; k < 2; ++k) dst[n][k] = *(const PG8_LAS bf16x8*)(lds + PG8_SB(b, h) + boff + n * 2048 + k * 1024); } while (0)
; #define PG8_MMA(ai, bj, At, Bt) do { __builtin_amdgcn_s_setprio(1); _Pragma("unroll") for (int m = 0; m < 4; ++m) _Pragma("unroll") for (int n = 0; n < 2; ++n) _Pragma("unroll") for (int k = 0; k < 2; ++k) \
;         acc[ai][bj][m][n] = __builtin_amdgcn_mfma_f32_16x16x32_bf16(Bt[n][k], At[m][k], acc[ai][bj][m][n], 0, 0, 0); __builtin_amdgcn_s_setprio(0); } while (0)
; #define PG8_WAIT_V(n) asm volatile("s_waitcnt vmcnt(" #n ")" ::: "memory")
; #define PG8_WAIT_L(n) asm volatile("s_waitcnt lgkmcnt(" #n ")" ::: "memory")
; #define PG8_BAR __builtin_amdgcn_s_barrier()
; #define PG8_SCHED __builtin_amdgcn_sched_barrier(0)
; template <class Epi, class Sched, bool ALIGN_EPI = false, bool SP2 = false>
; __device__ __forceinline__ void gemm_phase(PG8_LAS unsigned char* lds, const Gemm g, const Sched& S, const Epi& E) {
;     ...
;             PG8_WAIT_V(8); PG8_WAIT_L(0); PG8_BAR; PG8_MMA(1, 0, At, B0); PG8_MMA(1, 1, At, B1); PG8_BAR; PG8_SCHED;
;             PG8_LDB(B0, 1, 0); PG8_LDB(B1, 1, 1); PG8_SCHED; PG8_LDA(At, 1, 0); PG8_STAGE(PG8_SA(0, 1), a2 + hstep, voffA);
;             PG8_WAIT_V(8); PG8_WAIT_L(0); PG8_BAR; PG8_MMA(0, 0, At, B0); PG8_MMA(0, 1, At, B1); PG8_BAR; PG8_SCHED;
	v_mfma_f32_16x16x32_bf16 v[62:65], v[152:155], v[198:201], v[62:65]
	v_mfma_f32_16x16x32_bf16 v[58:61], v[172:175], v[198:201], v[58:61]
	v_mfma_f32_16x16x32_bf16 v[46:49], v[152:155], v[206:209], v[46:49]
	v_mfma_f32_16x16x32_bf16 v[42:45], v[172:175], v[206:209], v[42:45]
	v_mfma_f32_16x16x32_bf16 v[30:33], v[152:155], v[214:217], v[30:33]
	v_mfma_f32_16x16x32_bf16 v[26:29], v[172:175], v[214:217], v[26:29]
	v_mfma_f32_16x16x32_bf16 v[14:17], v[152:155], v[222:225], v[14:17]
	v_mfma_f32_16x16x32_bf16 v[10:13], v[172:175], v[222:225], v[10:13]
	v_mfma_f32_16x16x32_bf16 v[62:65], v[168:171], v[202:205], v[62:65]
	v_mfma_f32_16x16x32_bf16 v[58:61], v[176:179], v[202:205], v[58:61]
	v_mfma_f32_16x16x32_bf16 v[46:49], v[168:171], v[210:213], v[46:49]
	v_mfma_f32_16x16x32_bf16 v[42:45], v[176:179], v[210:213], v[42:45]
	v_mfma_f32_16x16x32_bf16 v[30:33], v[168:171], v[218:221], v[30:33]
	v_mfma_f32_16x16x32_bf16 v[26:29], v[176:179], v[218:221], v[26:29]
	v_mfma_f32_16x16x32_bf16 v[14:17], v[168:171], v[226:229], v[14:17]
	v_mfma_f32_16x16x32_bf16 v[10:13], v[176:179], v[226:229], v[10:13]
	s_setprio 0
	s_setprio 1
	v_mfma_f32_16x16x32_bf16 v[54:57], v[180:183], v[198:201], v[54:57]
	v_mfma_f32_16x16x32_bf16 v[50:53], v[188:191], v[198:201], v[50:53]
	v_mfma_f32_16x16x32_bf16 v[38:41], v[180:183], v[206:209], v[38:41]
	v_mfma_f32_16x16x32_bf16 v[34:37], v[188:191], v[206:209], v[34:37]
	v_mfma_f32_16x16x32_bf16 v[22:25], v[180:183], v[214:217], v[22:25]
	v_mfma_f32_16x16x32_bf16 v[18:21], v[188:191], v[214:217], v[18:21]
	v_mfma_f32_16x16x32_bf16 v[6:9], v[180:183], v[222:225], v[6:9]
	v_mfma_f32_16x16x32_bf16 v[2:5], v[188:191], v[222:225], v[2:5]
	v_mfma_f32_16x16x32_bf16 v[54:57], v[184:187], v[202:205], v[54:57]
	v_mfma_f32_16x16x32_bf16 v[50:53], v[192:195], v[202:205], v[50:53]
	v_mfma_f32_16x16x32_bf16 v[38:41], v[184:187], v[210:213], v[38:41]
	v_mfma_f32_16x16x32_bf16 v[34:37], v[192:195], v[210:213], v[34:37]
	v_mfma_f32_16x16x32_bf16 v[22:25], v[184:187], v[218:221], v[22:25]
	v_mfma_f32_16x16x32_bf16 v[18:21], v[192:195], v[218:221], v[18:21]
	v_mfma_f32_16x16x32_bf16 v[6:9], v[184:187], v[226:229], v[6:9]
	v_mfma_f32_16x16x32_bf16 v[2:5], v[192:195], v[226:229], v[2:5]
	s_barrier
	s_setprio 0
	s_add_i32 s81, 0, 0x18000
	v_add_u32_e32 v149, s81, v164
	s_add_i32 s82, 0, 0x1c000
	ds_read_b128 v[152:155], v149
	ds_read_b128 v[168:171], v149 offset:1024
	ds_read_b128 v[172:175], v149 offset:2048
	ds_read_b128 v[176:179], v149 offset:3072
	v_add_u32_e32 v149, s82, v164
	ds_read_b128 v[180:183], v149
	ds_read_b128 v[184:187], v149 offset:1024
	ds_read_b128 v[188:191], v149 offset:2048
	ds_read_b128 v[192:195], v149 offset:3072
	s_add_u32 s48, s48, 0x100000
	s_addc_u32 s49, s49, 0
	s_mov_b32 m0, s58
	v_lshl_add_u64 v[236:237], s[48:49], 0, v[130:131]
	ds_read_b128 v[198:201], v161 offset:32768
	ds_read_b128 v[202:205], v161 offset:33792
	ds_read_b128 v[206:209], v161 offset:34816
	ds_read_b128 v[210:213], v161 offset:35840
	ds_read_b128 v[214:217], v161 offset:36864
	ds_read_b128 v[218:221], v161 offset:37888
	ds_read_b128 v[222:225], v161 offset:38912
	ds_read_b128 v[226:229], v161 offset:39936
	global_load_lds_dwordx4 v[236:237], off
	v_lshl_add_u64 v[236:237], s[48:49], 0, v[134:135]
	s_mov_b32 m0, s59
	s_nop 0
	global_load_lds_dwordx4 v[236:237], off
	s_waitcnt vmcnt(8)
	s_waitcnt lgkmcnt(0)
	s_setprio 1
	s_barrier
	v_mfma_f32_16x16x32_bf16 v[126:129], v[152:155], v[198:201], v[126:129]
	v_mfma_f32_16x16x32_bf16 v[122:125], v[172:175], v[198:201], v[122:125]
	v_mfma_f32_16x16x32_bf16 v[110:113], v[152:155], v[206:209], v[110:113]
	v_mfma_f32_16x16x32_bf16 v[106:109], v[172:175], v[206:209], v[106:109]
	v_mfma_f32_16x16x32_bf16 v[94:97], v[152:155], v[214:217], v[94:97]
	v_mfma_f32_16x16x32_bf16 v[90:93], v[172:175], v[214:217], v[90:93]
	v_mfma_f32_16x16x32_bf16 v[78:81], v[152:155], v[222:225], v[78:81]
	v_mfma_f32_16x16x32_bf16 v[74:77], v[172:175], v[222:225], v[74:77]
	v_mfma_f32_16x16x32_bf16 v[126:129], v[168:171], v[202:205], v[126:129]
	v_mfma_f32_16x16x32_bf16 v[122:125], v[176:179], v[202:205], v[122:125]
	v_mfma_f32_16x16x32_bf16 v[110:113], v[168:171], v[210:213], v[110:113]
	v_mfma_f32_16x16x32_bf16 v[106:109], v[176:179], v[210:213], v[106:109]
	v_mfma_f32_16x16x32_bf16 v[94:97], v[168:171], v[218:221], v[94:97]
	v_mfma_f32_16x16x32_bf16 v[90:93], v[176:179], v[218:221], v[90:93]
	v_mfma_f32_16x16x32_bf16 v[78:81], v[168:171], v[226:229], v[78:81]
	v_mfma_f32_16x16x32_bf16 v[74:77], v[176:179], v[226:229], v[74:77]
	s_setprio 0
	s_setprio 1
	v_mfma_f32_16x16x32_bf16 v[118:121], v[180:183], v[198:201], v[118:121]
	v_mfma_f32_16x16x32_bf16 v[114:117], v[188:191], v[198:201], v[114:117]
	v_mfma_f32_16x16x32_bf16 v[102:105], v[180:183], v[206:209], v[102:105]
	v_mfma_f32_16x16x32_bf16 v[98:101], v[188:191], v[206:209], v[98:101]
	v_mfma_f32_16x16x32_bf16 v[86:89], v[180:183], v[214:217], v[86:89]
	v_mfma_f32_16x16x32_bf16 v[82:85], v[188:191], v[214:217], v[82:85]
	v_mfma_f32_16x16x32_bf16 v[70:73], v[180:183], v[222:225], v[70:73]
	v_mfma_f32_16x16x32_bf16 v[66:69], v[188:191], v[222:225], v[66:69]
	v_mfma_f32_16x16x32_bf16 v[118:121], v[184:187], v[202:205], v[118:121]
	v_mfma_f32_16x16x32_bf16 v[114:117], v[192:195], v[202:205], v[114:117]
	v_mfma_f32_16x16x32_bf16 v[102:105], v[184:187], v[210:213], v[102:105]
	v_mfma_f32_16x16x32_bf16 v[98:101], v[192:195], v[210:213], v[98:101]
	v_mfma_f32_16x16x32_bf16 v[86:89], v[184:187], v[218:221], v[86:89]
	v_mfma_f32_16x16x32_bf16 v[82:85], v[192:195], v[218:221], v[82:85]
	v_mfma_f32_16x16x32_bf16 v[70:73], v[184:187], v[226:229], v[70:73]
	v_mfma_f32_16x16x32_bf16 v[66:69], v[192:195], v[226:229], v[66:69]
	s_barrier
; #define PG8_STAGE(bufoff, gbase, voff) do { _Pragma("unroll") for (int _i = 0; _i < 2; ++_i) \
;         __builtin_amdgcn_global_load_lds((const unsigned*)((const char*)(gbase) + (voff)[_i]), (PG8_LAS unsigned*)(lds + (bufoff) + ldsw + _i * 8192), 16, 0, 0); } while (0)
; #define PG8_LDA(dst, b, h) do { _Pragma("unroll") for (int m = 0; m < 4; ++m) _Pragma("unroll") for (int k = 0; k < 2; ++k) dst[m][k] = *(const PG8_LAS bf16x8*)(lds + PG8_SA(b, h) + aoff + m * 2048 + k * 1024); } while (0)
; #define PG8_MMA(ai, bj, At, Bt) do { __builtin_amdgcn_s_setprio(1); _Pragma("unroll") for (int m = 0; m < 4; ++m) _Pragma("unroll") for (int n = 0; n < 2; ++n) _Pragma("unroll") for (int k = 0; k < 2; ++k) \
;         acc[ai][bj][m][n] = __builtin_amdgcn_mfma_f32_16x16x32_bf16(Bt[n][k], At[m][k], acc[ai][bj][m][n], 0, 0, 0); __builtin_amdgcn_s_setprio(0); } while (0)
; #define PG8_WAIT_V(n) asm volatile("s_waitcnt vmcnt(" #n ")" ::: "memory")
; #define PG8_WAIT_L(n) asm volatile("s_waitcnt lgkmcnt(" #n ")" ::: "memory")
; #define PG8_BAR __builtin_amdgcn_s_barrier()
; #define PG8_SCHED __builtin_amdgcn_sched_barrier(0)
; template <class Epi, class Sched, bool ALIGN_EPI = false, bool SP2 = false>
; __device__ __forceinline__ void gemm_phase(PG8_LAS unsigned char* lds, const Gemm g, const Sched& S, const Epi& E) {
;     ...
;             PG8_LDA(At, 1, 1); PG8_STAGE(PG8_SB(1, 0), b3, voffB); PG8_STAGE(PG8_SB(1, 1), b3 + hstep, voffB); PG8_STAGE(PG8_SA(1, 0), a3, voffA);
;             PG8_WAIT_V(8); PG8_WAIT_L(0); PG8_BAR; PG8_MMA(1, 0, At, B0); PG8_MMA(1, 1, At, B1); PG8_BAR; PG8_SCHED;
;     ...
;         if constexpr (ALIGN_EPI) { if (wr == 0) PG8_BAR; }
	s_setprio 0
	s_add_i32 s48, s81, s55
	v_lshl_add_u64 v[156:157], v[156:157], 0, s[10:11]
	s_mov_b32 m0, s48
	ds_read_b128 v[198:201], v161 offset:49152
	ds_read_b128 v[202:205], v161 offset:50176
	ds_read_b128 v[206:209], v161 offset:51200
	ds_read_b128 v[210:213], v161 offset:52224
	ds_read_b128 v[214:217], v161 offset:53248
	ds_read_b128 v[218:221], v161 offset:54272
	ds_read_b128 v[222:225], v161 offset:55296
	ds_read_b128 v[226:229], v161 offset:56320
	global_load_lds_dwordx4 v[156:157], off
	s_add_i32 m0, s48, 0x2000
	s_add_u32 s46, s46, 0x100080
	v_lshl_add_u64 v[156:157], v[230:231], 0, s[10:11]
	s_addc_u32 s47, s47, 0
	s_add_i32 s48, s82, s55
	global_load_lds_dwordx4 v[156:157], off
	v_lshl_add_u64 v[156:157], s[46:47], 0, v[132:133]
	s_mov_b32 m0, s48
	s_nop 0
	global_load_lds_dwordx4 v[156:157], off
	v_lshl_add_u64 v[156:157], s[46:47], 0, v[136:137]
	s_add_i32 m0, s48, 0x2000
	s_nop 0
	global_load_lds_dwordx4 v[156:157], off
	v_lshl_add_u64 v[156:157], v[232:233], 0, s[10:11]
	s_mov_b32 m0, s70
	s_nop 0
	global_load_lds_dwordx4 v[156:157], off
	v_lshl_add_u64 v[156:157], v[234:235], 0, s[10:11]
	s_mov_b32 m0, s71
	s_nop 0
	global_load_lds_dwordx4 v[156:157], off
	s_waitcnt vmcnt(8)
	s_waitcnt lgkmcnt(0)
	s_setprio 1
	s_barrier
	v_mfma_f32_16x16x32_bf16 v[62:65], v[152:155], v[198:201], v[62:65]
	v_mfma_f32_16x16x32_bf16 v[58:61], v[172:175], v[198:201], v[58:61]
	v_mfma_f32_16x16x32_bf16 v[46:49], v[152:155], v[206:209], v[46:49]
	v_mfma_f32_16x16x32_bf16 v[42:45], v[172:175], v[206:209], v[42:45]
	v_mfma_f32_16x16x32_bf16 v[30:33], v[152:155], v[214:217], v[30:33]
	v_mfma_f32_16x16x32_bf16 v[26:29], v[172:175], v[214:217], v[26:29]
	v_mfma_f32_16x16x32_bf16 v[14:17], v[152:155], v[222:225], v[14:17]
	v_mfma_f32_16x16x32_bf16 v[10:13], v[172:175], v[222:225], v[10:13]
	v_mfma_f32_16x16x32_bf16 v[62:65], v[168:171], v[202:205], v[62:65]
	v_mfma_f32_16x16x32_bf16 v[58:61], v[176:179], v[202:205], v[58:61]
	v_mfma_f32_16x16x32_bf16 v[46:49], v[168:171], v[210:213], v[46:49]
	v_mfma_f32_16x16x32_bf16 v[42:45], v[176:179], v[210:213], v[42:45]
	v_mfma_f32_16x16x32_bf16 v[30:33], v[168:171], v[218:221], v[30:33]
	v_mfma_f32_16x16x32_bf16 v[26:29], v[176:179], v[218:221], v[26:29]
	v_mfma_f32_16x16x32_bf16 v[14:17], v[168:171], v[226:229], v[14:17]
	v_mfma_f32_16x16x32_bf16 v[10:13], v[176:179], v[226:229], v[10:13]
	s_setprio 0
	s_setprio 1
	v_mfma_f32_16x16x32_bf16 v[54:57], v[180:183], v[198:201], v[54:57]
	v_mfma_f32_16x16x32_bf16 v[50:53], v[188:191], v[198:201], v[50:53]
	v_mfma_f32_16x16x32_bf16 v[38:41], v[180:183], v[206:209], v[38:41]
	v_mfma_f32_16x16x32_bf16 v[34:37], v[188:191], v[206:209], v[34:37]
	v_mfma_f32_16x16x32_bf16 v[22:25], v[180:183], v[214:217], v[22:25]
	v_mfma_f32_16x16x32_bf16 v[18:21], v[188:191], v[214:217], v[18:21]
	v_mfma_f32_16x16x32_bf16 v[6:9], v[180:183], v[222:225], v[6:9]
	v_mfma_f32_16x16x32_bf16 v[2:5], v[188:191], v[222:225], v[2:5]
	v_mfma_f32_16x16x32_bf16 v[54:57], v[184:187], v[202:205], v[54:57]
	v_mfma_f32_16x16x32_bf16 v[50:53], v[192:195], v[202:205], v[50:53]
	v_mfma_f32_16x16x32_bf16 v[38:41], v[184:187], v[210:213], v[38:41]
	v_mfma_f32_16x16x32_bf16 v[34:37], v[192:195], v[210:213], v[34:37]
	v_mfma_f32_16x16x32_bf16 v[22:25], v[184:187], v[218:221], v[22:25]
	v_mfma_f32_16x16x32_bf16 v[18:21], v[192:195], v[218:221], v[18:21]
	v_mfma_f32_16x16x32_bf16 v[6:9], v[184:187], v[226:229], v[6:9]
	v_mfma_f32_16x16x32_bf16 v[2:5], v[192:195], v[226:229], v[2:5]
	s_barrier
	s_setprio 0
	s_add_i32 s80, s80, 2
	s_add_u32 s44, s44, 0x100
	s_addc_u32 s45, s45, 0
	s_add_u32 s78, s78, 0x100
	s_addc_u32 s79, s79, 0
	s_cmp_gt_u32 s80, 61
	s_cbranch_scc0 .LBB0_217
	s_and_b64 vcc, exec, s[12:13]
	s_cbranch_vccz .LBB0_220
	s_barrier

; #define PG8_STAGE(bufoff, gbase, voff) do { _Pragma("unroll") for (int _i = 0; _i < 2; ++_i) \
;         __builtin_amdgcn_global_load_lds((const unsigned*)((const char*)(gbase) + (voff)[_i]), (PG8_LAS unsigned*)(lds + (bufoff) + ldsw + _i * 8192), 16, 0, 0); } while (0)
; #define PG8_LDA(dst, b, h) do { _Pragma("unroll") for (int m = 0; m < 4; ++m) _Pragma("unroll") for (int k = 0; k < 2; ++k) dst[m][k] = *(const PG8_LAS bf16x8*)(lds + PG8_SA(b, h) + aoff + m * 2048 + k * 1024); } while (0)
; #define PG8_LDB(dst, b, h) do { _Pragma("unroll") for (int n = 0; n < 2; ++n) _Pragma("unroll") for (int k = 0; k < 2; ++k) dst[n][k] = *(const PG8_LAS bf16x8*)(lds + PG8_SB(b, h) + boff + n * 2048 + k * 1024); } while (0)
; #define PG8_MMA(ai, bj, At, Bt) do { __builtin_amdgcn_s_setprio(1); _Pragma("unroll") for (int m = 0; m < 4; ++m) _Pragma("unroll") for (int n = 0; n < 2; ++n) _Pragma("unroll") for (int k = 0; k < 2; ++k) \
;         acc[ai][bj][m][n] = __builtin_amdgcn_mfma_f32_16x16x32_bf16(Bt[n][k], At[m][k], acc[ai][bj][m][n], 0, 0, 0); __builtin_amdgcn_s_setprio(0); } while (0)
; #define PG8_WAIT_V(n) asm volatile("s_waitcnt vmcnt(" #n ")" ::: "memory")
; #define PG8_WAIT_L(n) asm volatile("s_waitcnt lgkmcnt(" #n ")" ::: "memory")
; #define PG8_BAR __builtin_amdgcn_s_barrier()
; #define PG8_SCHED __builtin_amdgcn_sched_barrier(0)
; template <class Epi, class Sched, bool ALIGN_EPI = false, bool SP2 = false>
; __device__ __forceinline__ void gemm_phase(PG8_LAS unsigned char* lds, const Gemm g, const Sched& S, const Epi& E) {
;     ...
;             PG8_LDB(B0, 0, 0); PG8_LDB(B1, 0, 1); PG8_SCHED; PG8_LDA(At, 0, 0); PG8_STAGE(PG8_SA(1, 1), a1 + hstep, voffA);
;             PG8_WAIT_V(8); PG8_WAIT_L(0); PG8_BAR; PG8_MMA(0, 0, At, B0); PG8_MMA(0, 1, At, B1); PG8_BAR; PG8_SCHED;
;             PG8_LDA(At, 0, 1); PG8_STAGE(PG8_SB(0, 0), b2, voffB); PG8_STAGE(PG8_SB(0, 1), b2 + hstep, voffB); PG8_STAGE(PG8_SA(0, 0), a2, voffA);
;             PG8_WAIT_V(8); PG8_WAIT_L(0); PG8_BAR; PG8_MMA(1, 0, At, B0); PG8_MMA(1, 1, At, B1); PG8_BAR; PG8_SCHED;
.LBB0_710:
	ds_read_b128 v[146:149], v160
	ds_read_b128 v[164:167], v160 offset:1024
	ds_read_b128 v[168:171], v160 offset:2048
	ds_read_b128 v[172:175], v160 offset:3072
	ds_read_b128 v[176:179], v161
	ds_read_b128 v[180:183], v161 offset:1024
	ds_read_b128 v[184:187], v161 offset:2048
	ds_read_b128 v[188:191], v161 offset:3072
	s_add_u32 s50, s48, 0xfff00080
	s_addc_u32 s51, s49, -1
	s_cmp_eq_u32 s76, 60
	s_cselect_b32 s53, s43, s51
	s_cselect_b32 s52, s72, s50
	s_cselect_b32 s51, s41, s75
	s_cselect_b32 s50, s73, s74
	v_lshl_add_u64 v[226:227], s[48:49], 0, v[138:139]
	s_add_i32 m0, s9, 0xc000
	ds_read_b128 v[192:195], v162
	ds_read_b128 v[198:201], v162 offset:1024
	ds_read_b128 v[202:205], v162 offset:2048
	ds_read_b128 v[206:209], v162 offset:3072
	ds_read_b128 v[210:213], v162 offset:4096
	ds_read_b128 v[214:217], v162 offset:5120
	ds_read_b128 v[218:221], v162 offset:6144
	ds_read_b128 v[222:225], v162 offset:7168
	global_load_lds_dwordx4 v[226:227], off
	v_lshl_add_u64 v[226:227], s[48:49], 0, v[140:141]
	s_add_i32 m0, s9, 0xe000
	s_nop 0
	global_load_lds_dwordx4 v[226:227], off
	s_waitcnt vmcnt(8)
	s_waitcnt lgkmcnt(0)
	s_setprio 1
	s_barrier
	v_mfma_f32_16x16x32_bf16 v[126:129], v[146:149], v[192:195], v[126:129]
	v_mfma_f32_16x16x32_bf16 v[122:125], v[168:171], v[192:195], v[122:125]
	v_mfma_f32_16x16x32_bf16 v[110:113], v[146:149], v[202:205], v[110:113]
	v_mfma_f32_16x16x32_bf16 v[106:109], v[168:171], v[202:205], v[106:109]
	v_mfma_f32_16x16x32_bf16 v[94:97], v[146:149], v[210:213], v[94:97]
	v_mfma_f32_16x16x32_bf16 v[90:93], v[168:171], v[210:213], v[90:93]
	v_mfma_f32_16x16x32_bf16 v[78:81], v[146:149], v[218:221], v[78:81]
	v_mfma_f32_16x16x32_bf16 v[74:77], v[168:171], v[218:221], v[74:77]
	v_mfma_f32_16x16x32_bf16 v[126:129], v[164:167], v[198:201], v[126:129]
	v_mfma_f32_16x16x32_bf16 v[122:125], v[172:175], v[198:201], v[122:125]
	v_mfma_f32_16x16x32_bf16 v[110:113], v[164:167], v[206:209], v[110:113]
	v_mfma_f32_16x16x32_bf16 v[106:109], v[172:175], v[206:209], v[106:109]
	v_mfma_f32_16x16x32_bf16 v[94:97], v[164:167], v[214:217], v[94:97]
	v_mfma_f32_16x16x32_bf16 v[90:93], v[172:175], v[214:217], v[90:93]
	v_mfma_f32_16x16x32_bf16 v[78:81], v[164:167], v[222:225], v[78:81]
	v_mfma_f32_16x16x32_bf16 v[74:77], v[172:175], v[222:225], v[74:77]
	s_setprio 0
	s_setprio 1
	v_mfma_f32_16x16x32_bf16 v[118:121], v[176:179], v[192:195], v[118:121]
	v_mfma_f32_16x16x32_bf16 v[114:117], v[184:187], v[192:195], v[114:117]
	v_mfma_f32_16x16x32_bf16 v[102:105], v[176:179], v[202:205], v[102:105]
	v_mfma_f32_16x16x32_bf16 v[98:101], v[184:187], v[202:205], v[98:101]
	v_mfma_f32_16x16x32_bf16 v[86:89], v[176:179], v[210:213], v[86:89]
	v_mfma_f32_16x16x32_bf16 v[82:85], v[184:187], v[210:213], v[82:85]
	v_mfma_f32_16x16x32_bf16 v[70:73], v[176:179], v[218:221], v[70:73]
	v_mfma_f32_16x16x32_bf16 v[66:69], v[184:187], v[218:221], v[66:69]
	v_mfma_f32_16x16x32_bf16 v[118:121], v[180:183], v[198:201], v[118:121]
	v_mfma_f32_16x16x32_bf16 v[114:117], v[188:191], v[198:201], v[114:117]
	v_mfma_f32_16x16x32_bf16 v[102:105], v[180:183], v[206:209], v[102:105]
	v_mfma_f32_16x16x32_bf16 v[98:101], v[188:191], v[206:209], v[98:101]
	v_mfma_f32_16x16x32_bf16 v[86:89], v[180:183], v[214:217], v[86:89]
	v_mfma_f32_16x16x32_bf16 v[82:85], v[188:191], v[214:217], v[82:85]
	v_mfma_f32_16x16x32_bf16 v[70:73], v[180:183], v[222:225], v[70:73]
	v_mfma_f32_16x16x32_bf16 v[66:69], v[188:191], v[222:225], v[66:69]
	s_barrier
	s_setprio 0
	s_add_i32 s77, s69, s56
	v_lshl_add_u64 v[226:227], s[50:51], 0, v[132:133]
	s_mov_b32 m0, s77
	ds_read_b128 v[192:195], v162 offset:16384
	ds_read_b128 v[198:201], v162 offset:17408
	ds_read_b128 v[202:205], v162 offset:18432
	ds_read_b128 v[206:209], v162 offset:19456
	ds_read_b128 v[210:213], v162 offset:20480
	ds_read_b128 v[214:217], v162 offset:21504
	ds_read_b128 v[218:221], v162 offset:22528
	ds_read_b128 v[222:225], v162 offset:23552
	global_load_lds_dwordx4 v[226:227], off
	s_add_i32 m0, s77, 0x2000
	s_add_u32 s78, s50, 0x100000
	v_lshl_add_u64 v[228:229], s[50:51], 0, v[136:137]
	s_addc_u32 s79, s51, 0
	s_add_i32 s77, s70, s56
	global_load_lds_dwordx4 v[228:229], off
	v_lshl_add_u64 v[230:231], s[78:79], 0, v[132:133]
	s_mov_b32 m0, s77
	v_lshl_add_u64 v[232:233], s[52:53], 0, v[134:135]
	global_load_lds_dwordx4 v[230:231], off
	v_lshl_add_u64 v[230:231], s[78:79], 0, v[136:137]
	s_add_i32 m0, s77, 0x2000
	s_nop 0
	global_load_lds_dwordx4 v[230:231], off
	v_lshl_add_u64 v[230:231], s[52:53], 0, v[130:131]
	s_mov_b32 m0, s9
	s_nop 0
	global_load_lds_dwordx4 v[230:231], off
	s_mov_b32 m0, s57
	s_nop 0
	global_load_lds_dwordx4 v[232:233], off
	s_waitcnt vmcnt(8)
	s_waitcnt lgkmcnt(0)
	s_setprio 1
	s_barrier
; #define PG8_STAGE(bufoff, gbase, voff) do { _Pragma("unroll") for (int _i = 0; _i < 2; ++_i) \
;         __builtin_amdgcn_global_load_lds((const unsigned*)((const char*)(gbase) + (voff)[_i]), (PG8_LAS unsigned*)(lds + (bufoff) + ldsw + _i * 8192), 16, 0, 0); } while (0)
; #define PG8_LDA(dst, b, h) do { _Pragma("unroll") for (int m = 0; m < 4; ++m) _Pragma("unroll") for (int k = 0; k < 2; ++k) dst[m][k] = *(const PG8_LAS bf16x8*)(lds + PG8_SA(b, h) + aoff + m * 2048 + k * 1024); } while (0)
; #define PG8_LDB(dst, b, h) do { _Pragma("unroll") for (int n = 0; n < 2; ++n) _Pragma("unroll") for (int k = 0; k < 2; ++k) dst[n][k] = *(const PG8_LAS bf16x8*)(lds + PG8_SB(b, h) + boff + n * 2048 + k * 1024); } while (0)
; #define PG8_MMA(ai, bj, At, Bt) do { __builtin_amdgcn_s_setprio(1); _Pragma("unroll") for (int m = 0; m < 4; ++m) _Pragma("unroll") for (int n = 0; n < 2; ++n) _Pragma("unroll") for (int k = 0; k < 2; ++k) \
;         acc[ai][bj][m][n] = __builtin_amdgcn_mfma_f32_16x16x32_bf16(Bt[n][k], At[m][k], acc[ai][bj][m][n], 0, 0, 0); __builtin_amdgcn_s_setprio(0); } while (0)
; #define PG8_WAIT_V(n) asm volatile("s_waitcnt vmcnt(" #n ")" ::: "memory")
; #define PG8_WAIT_L(n) asm volatile("s_waitcnt lgkmcnt(" #n ")" ::: "memory")
; #define PG8_BAR __builtin_amdgcn_s_barrier()
; #define PG8_SCHED __builtin_amdgcn_sched_barrier(0)
; template <class Epi, class Sched, bool ALIGN_EPI = false, bool SP2 = false>
; __device__ __forceinline__ void gemm_phase(PG8_LAS unsigned char* lds, const Gemm g, const Sched& S, const Epi& E) {
;     ...
;             PG8_WAIT_V(8); PG8_WAIT_L(0); PG8_BAR; PG8_MMA(1, 0, At, B0); PG8_MMA(1, 1, At, B1); PG8_BAR; PG8_SCHED;
;             PG8_LDB(B0, 1, 0); PG8_LDB(B1, 1, 1); PG8_SCHED; PG8_LDA(At, 1, 0); PG8_STAGE(PG8_SA(0, 1), a2 + hstep, voffA);
;             PG8_WAIT_V(8); PG8_WAIT_L(0); PG8_BAR; PG8_MMA(0, 0, At, B0); PG8_MMA(0, 1, At, B1); PG8_BAR; PG8_SCHED;
	v_mfma_f32_16x16x32_bf16 v[62:65], v[146:149], v[192:195], v[62:65]
	v_mfma_f32_16x16x32_bf16 v[58:61], v[168:171], v[192:195], v[58:61]
	v_mfma_f32_16x16x32_bf16 v[46:49], v[146:149], v[202:205], v[46:49]
	v_mfma_f32_16x16x32_bf16 v[42:45], v[168:171], v[202:205], v[42:45]
	v_mfma_f32_16x16x32_bf16 v[30:33], v[146:149], v[210:213], v[30:33]
	v_mfma_f32_16x16x32_bf16 v[26:29], v[168:171], v[210:213], v[26:29]
	v_mfma_f32_16x16x32_bf16 v[14:17], v[146:149], v[218:221], v[14:17]
	v_mfma_f32_16x16x32_bf16 v[10:13], v[168:171], v[218:221], v[10:13]
	v_mfma_f32_16x16x32_bf16 v[62:65], v[164:167], v[198:201], v[62:65]
	v_mfma_f32_16x16x32_bf16 v[58:61], v[172:175], v[198:201], v[58:61]
	v_mfma_f32_16x16x32_bf16 v[46:49], v[164:167], v[206:209], v[46:49]
	v_mfma_f32_16x16x32_bf16 v[42:45], v[172:175], v[206:209], v[42:45]
	v_mfma_f32_16x16x32_bf16 v[30:33], v[164:167], v[214:217], v[30:33]
	v_mfma_f32_16x16x32_bf16 v[26:29], v[172:175], v[214:217], v[26:29]
	v_mfma_f32_16x16x32_bf16 v[14:17], v[164:167], v[222:225], v[14:17]
	v_mfma_f32_16x16x32_bf16 v[10:13], v[172:175], v[222:225], v[10:13]
	s_setprio 0
	s_setprio 1
	v_mfma_f32_16x16x32_bf16 v[54:57], v[176:179], v[192:195], v[54:57]
	v_mfma_f32_16x16x32_bf16 v[50:53], v[184:187], v[192:195], v[50:53]
	v_mfma_f32_16x16x32_bf16 v[38:41], v[176:179], v[202:205], v[38:41]
	v_mfma_f32_16x16x32_bf16 v[34:37], v[184:187], v[202:205], v[34:37]
	v_mfma_f32_16x16x32_bf16 v[22:25], v[176:179], v[210:213], v[22:25]
	v_mfma_f32_16x16x32_bf16 v[18:21], v[184:187], v[210:213], v[18:21]
	v_mfma_f32_16x16x32_bf16 v[6:9], v[176:179], v[218:221], v[6:9]
	v_mfma_f32_16x16x32_bf16 v[2:5], v[184:187], v[218:221], v[2:5]
	v_mfma_f32_16x16x32_bf16 v[54:57], v[180:183], v[198:201], v[54:57]
	v_mfma_f32_16x16x32_bf16 v[50:53], v[188:191], v[198:201], v[50:53]
	v_mfma_f32_16x16x32_bf16 v[38:41], v[180:183], v[206:209], v[38:41]
	v_mfma_f32_16x16x32_bf16 v[34:37], v[188:191], v[206:209], v[34:37]
	v_mfma_f32_16x16x32_bf16 v[22:25], v[180:183], v[214:217], v[22:25]
	v_mfma_f32_16x16x32_bf16 v[18:21], v[188:191], v[214:217], v[18:21]
	v_mfma_f32_16x16x32_bf16 v[6:9], v[180:183], v[222:225], v[6:9]
	v_mfma_f32_16x16x32_bf16 v[2:5], v[188:191], v[222:225], v[2:5]
	s_barrier
	s_setprio 0
	s_add_i32 s77, 0, 0x18000
	s_add_i32 s78, 0, 0x1c000
	v_add_u32_e32 v172, s77, v151
	v_add_u32_e32 v188, s78, v151
	ds_read_b128 v[146:149], v172
	ds_read_b128 v[164:167], v172 offset:1024
	ds_read_b128 v[168:171], v172 offset:2048
	ds_read_b128 v[172:175], v172 offset:3072
	ds_read_b128 v[176:179], v188
	ds_read_b128 v[180:183], v188 offset:1024
	ds_read_b128 v[184:187], v188 offset:2048
	ds_read_b128 v[188:191], v188 offset:3072
	s_add_u32 s52, s52, 0x100000
	s_addc_u32 s53, s53, 0
	s_mov_b32 m0, s58
	v_lshl_add_u64 v[234:235], s[52:53], 0, v[130:131]
	ds_read_b128 v[192:195], v162 offset:32768
	ds_read_b128 v[198:201], v162 offset:33792
	ds_read_b128 v[202:205], v162 offset:34816
	ds_read_b128 v[206:209], v162 offset:35840
	ds_read_b128 v[210:213], v162 offset:36864
	ds_read_b128 v[214:217], v162 offset:37888
	ds_read_b128 v[218:221], v162 offset:38912
	ds_read_b128 v[222:225], v162 offset:39936
	global_load_lds_dwordx4 v[234:235], off
	v_lshl_add_u64 v[234:235], s[52:53], 0, v[134:135]
	s_mov_b32 m0, s59
	s_nop 0
	global_load_lds_dwordx4 v[234:235], off
	s_waitcnt vmcnt(8)
	s_waitcnt lgkmcnt(0)
	s_setprio 1
	s_barrier
	v_mfma_f32_16x16x32_bf16 v[126:129], v[146:149], v[192:195], v[126:129]
	v_mfma_f32_16x16x32_bf16 v[122:125], v[168:171], v[192:195], v[122:125]
	v_mfma_f32_16x16x32_bf16 v[110:113], v[146:149], v[202:205], v[110:113]
	v_mfma_f32_16x16x32_bf16 v[106:109], v[168:171], v[202:205], v[106:109]
	v_mfma_f32_16x16x32_bf16 v[94:97], v[146:149], v[210:213], v[94:97]
	v_mfma_f32_16x16x32_bf16 v[90:93], v[168:171], v[210:213], v[90:93]
	v_mfma_f32_16x16x32_bf16 v[78:81], v[146:149], v[218:221], v[78:81]
	v_mfma_f32_16x16x32_bf16 v[74:77], v[168:171], v[218:221], v[74:77]
	v_mfma_f32_16x16x32_bf16 v[126:129], v[164:167], v[198:201], v[126:129]
	v_mfma_f32_16x16x32_bf16 v[122:125], v[172:175], v[198:201], v[122:125]
	v_mfma_f32_16x16x32_bf16 v[110:113], v[164:167], v[206:209], v[110:113]
	v_mfma_f32_16x16x32_bf16 v[106:109], v[172:175], v[206:209], v[106:109]
	v_mfma_f32_16x16x32_bf16 v[94:97], v[164:167], v[214:217], v[94:97]
	v_mfma_f32_16x16x32_bf16 v[90:93], v[172:175], v[214:217], v[90:93]
	v_mfma_f32_16x16x32_bf16 v[78:81], v[164:167], v[222:225], v[78:81]
	v_mfma_f32_16x16x32_bf16 v[74:77], v[172:175], v[222:225], v[74:77]
	s_setprio 0
	s_setprio 1
	v_mfma_f32_16x16x32_bf16 v[118:121], v[176:179], v[192:195], v[118:121]
	v_mfma_f32_16x16x32_bf16 v[114:117], v[184:187], v[192:195], v[114:117]
	v_mfma_f32_16x16x32_bf16 v[102:105], v[176:179], v[202:205], v[102:105]
	v_mfma_f32_16x16x32_bf16 v[98:101], v[184:187], v[202:205], v[98:101]
	v_mfma_f32_16x16x32_bf16 v[86:89], v[176:179], v[210:213], v[86:89]
	v_mfma_f32_16x16x32_bf16 v[82:85], v[184:187], v[210:213], v[82:85]
	v_mfma_f32_16x16x32_bf16 v[70:73], v[176:179], v[218:221], v[70:73]
	v_mfma_f32_16x16x32_bf16 v[66:69], v[184:187], v[218:221], v[66:69]
	v_mfma_f32_16x16x32_bf16 v[118:121], v[180:183], v[198:201], v[118:121]
	v_mfma_f32_16x16x32_bf16 v[114:117], v[188:191], v[198:201], v[114:117]
	v_mfma_f32_16x16x32_bf16 v[102:105], v[180:183], v[206:209], v[102:105]
	v_mfma_f32_16x16x32_bf16 v[98:101], v[188:191], v[206:209], v[98:101]
	v_mfma_f32_16x16x32_bf16 v[86:89], v[180:183], v[214:217], v[86:89]
	v_mfma_f32_16x16x32_bf16 v[82:85], v[188:191], v[214:217], v[82:85]
	v_mfma_f32_16x16x32_bf16 v[70:73], v[180:183], v[222:225], v[70:73]
	v_mfma_f32_16x16x32_bf16 v[66:69], v[188:191], v[222:225], v[66:69]
	s_barrier
; #define PG8_STAGE(bufoff, gbase, voff) do { _Pragma("unroll") for (int _i = 0; _i < 2; ++_i) \
;         __builtin_amdgcn_global_load_lds((const unsigned*)((const char*)(gbase) + (voff)[_i]), (PG8_LAS unsigned*)(lds + (bufoff) + ldsw + _i * 8192), 16, 0, 0); } while (0)
; #define PG8_LDA(dst, b, h) do { _Pragma("unroll") for (int m = 0; m < 4; ++m) _Pragma("unroll") for (int k = 0; k < 2; ++k) dst[m][k] = *(const PG8_LAS bf16x8*)(lds + PG8_SA(b, h) + aoff + m * 2048 + k * 1024); } while (0)
; #define PG8_MMA(ai, bj, At, Bt) do { __builtin_amdgcn_s_setprio(1); _Pragma("unroll") for (int m = 0; m < 4; ++m) _Pragma("unroll") for (int n = 0; n < 2; ++n) _Pragma("unroll") for (int k = 0; k < 2; ++k) \
;         acc[ai][bj][m][n] = __builtin_amdgcn_mfma_f32_16x16x32_bf16(Bt[n][k], At[m][k], acc[ai][bj][m][n], 0, 0, 0); __builtin_amdgcn_s_setprio(0); } while (0)
; #define PG8_WAIT_V(n) asm volatile("s_waitcnt vmcnt(" #n ")" ::: "memory")
; #define PG8_WAIT_L(n) asm volatile("s_waitcnt lgkmcnt(" #n ")" ::: "memory")
; #define PG8_BAR __builtin_amdgcn_s_barrier()
; #define PG8_SCHED __builtin_amdgcn_sched_barrier(0)
; template <class Epi, class Sched, bool ALIGN_EPI = false, bool SP2 = false>
; __device__ __forceinline__ void gemm_phase(PG8_LAS unsigned char* lds, const Gemm g, const Sched& S, const Epi& E) {
;     ...
;             PG8_LDA(At, 1, 1); PG8_STAGE(PG8_SB(1, 0), b3, voffB); PG8_STAGE(PG8_SB(1, 1), b3 + hstep, voffB); PG8_STAGE(PG8_SA(1, 0), a3, voffA);
;             PG8_WAIT_V(8); PG8_WAIT_L(0); PG8_BAR; PG8_MMA(1, 0, At, B0); PG8_MMA(1, 1, At, B1); PG8_BAR; PG8_SCHED;
;     ...
;         if constexpr (ALIGN_EPI) { if (wr == 0) PG8_BAR; }
	s_setprio 0
	s_add_i32 s52, s77, s56
	v_lshl_add_u64 v[226:227], v[226:227], 0, s[36:37]
	s_mov_b32 m0, s52
	ds_read_b128 v[192:195], v162 offset:49152
	ds_read_b128 v[198:201], v162 offset:50176
	ds_read_b128 v[202:205], v162 offset:51200
	ds_read_b128 v[206:209], v162 offset:52224
	ds_read_b128 v[210:213], v162 offset:53248
	ds_read_b128 v[214:217], v162 offset:54272
	ds_read_b128 v[218:221], v162 offset:55296
	ds_read_b128 v[222:225], v162 offset:56320
	global_load_lds_dwordx4 v[226:227], off
	s_add_i32 m0, s52, 0x2000
	s_add_u32 s50, s50, 0x100080
	v_lshl_add_u64 v[226:227], v[228:229], 0, s[36:37]
	s_addc_u32 s51, s51, 0
	s_add_i32 s52, s78, s56
	global_load_lds_dwordx4 v[226:227], off
	v_lshl_add_u64 v[226:227], s[50:51], 0, v[132:133]
	s_mov_b32 m0, s52
	s_nop 0
	global_load_lds_dwordx4 v[226:227], off
	v_lshl_add_u64 v[226:227], s[50:51], 0, v[136:137]
	s_add_i32 m0, s52, 0x2000
	s_nop 0
	global_load_lds_dwordx4 v[226:227], off
	v_lshl_add_u64 v[226:227], v[230:231], 0, s[36:37]
	s_mov_b32 m0, s61
	s_nop 0
	global_load_lds_dwordx4 v[226:227], off
	v_lshl_add_u64 v[226:227], v[232:233], 0, s[36:37]
	s_mov_b32 m0, s62
	s_nop 0
	global_load_lds_dwordx4 v[226:227], off
	s_waitcnt vmcnt(8)
	s_waitcnt lgkmcnt(0)
	s_setprio 1
	s_barrier
	v_mfma_f32_16x16x32_bf16 v[62:65], v[146:149], v[192:195], v[62:65]
	v_mfma_f32_16x16x32_bf16 v[58:61], v[168:171], v[192:195], v[58:61]
	v_mfma_f32_16x16x32_bf16 v[46:49], v[146:149], v[202:205], v[46:49]
	v_mfma_f32_16x16x32_bf16 v[42:45], v[168:171], v[202:205], v[42:45]
	v_mfma_f32_16x16x32_bf16 v[30:33], v[146:149], v[210:213], v[30:33]
	v_mfma_f32_16x16x32_bf16 v[26:29], v[168:171], v[210:213], v[26:29]
	v_mfma_f32_16x16x32_bf16 v[14:17], v[146:149], v[218:221], v[14:17]
	v_mfma_f32_16x16x32_bf16 v[10:13], v[168:171], v[218:221], v[10:13]
	v_mfma_f32_16x16x32_bf16 v[62:65], v[164:167], v[198:201], v[62:65]
	v_mfma_f32_16x16x32_bf16 v[58:61], v[172:175], v[198:201], v[58:61]
	v_mfma_f32_16x16x32_bf16 v[46:49], v[164:167], v[206:209], v[46:49]
	v_mfma_f32_16x16x32_bf16 v[42:45], v[172:175], v[206:209], v[42:45]
	v_mfma_f32_16x16x32_bf16 v[30:33], v[164:167], v[214:217], v[30:33]
	v_mfma_f32_16x16x32_bf16 v[26:29], v[172:175], v[214:217], v[26:29]
	v_mfma_f32_16x16x32_bf16 v[14:17], v[164:167], v[222:225], v[14:17]
	v_mfma_f32_16x16x32_bf16 v[10:13], v[172:175], v[222:225], v[10:13]
	s_setprio 0
	s_setprio 1
	v_mfma_f32_16x16x32_bf16 v[54:57], v[176:179], v[192:195], v[54:57]
	v_mfma_f32_16x16x32_bf16 v[50:53], v[184:187], v[192:195], v[50:53]
	v_mfma_f32_16x16x32_bf16 v[38:41], v[176:179], v[202:205], v[38:41]
	v_mfma_f32_16x16x32_bf16 v[34:37], v[184:187], v[202:205], v[34:37]
	v_mfma_f32_16x16x32_bf16 v[22:25], v[176:179], v[210:213], v[22:25]
	v_mfma_f32_16x16x32_bf16 v[18:21], v[184:187], v[210:213], v[18:21]
	v_mfma_f32_16x16x32_bf16 v[6:9], v[176:179], v[218:221], v[6:9]
	v_mfma_f32_16x16x32_bf16 v[2:5], v[184:187], v[218:221], v[2:5]
	v_mfma_f32_16x16x32_bf16 v[54:57], v[180:183], v[198:201], v[54:57]
	v_mfma_f32_16x16x32_bf16 v[50:53], v[188:191], v[198:201], v[50:53]
	v_mfma_f32_16x16x32_bf16 v[38:41], v[180:183], v[206:209], v[38:41]
	v_mfma_f32_16x16x32_bf16 v[34:37], v[188:191], v[206:209], v[34:37]
	v_mfma_f32_16x16x32_bf16 v[22:25], v[180:183], v[214:217], v[22:25]
	v_mfma_f32_16x16x32_bf16 v[18:21], v[188:191], v[214:217], v[18:21]
	v_mfma_f32_16x16x32_bf16 v[6:9], v[180:183], v[222:225], v[6:9]
	v_mfma_f32_16x16x32_bf16 v[2:5], v[188:191], v[222:225], v[2:5]
	s_barrier
	s_setprio 0
	s_add_i32 s76, s76, 2
	s_add_u32 s48, s48, 0x100
	s_addc_u32 s49, s49, 0
	s_add_u32 s74, s74, 0x100
	s_addc_u32 s75, s75, 0
	s_cmp_gt_u32 s76, 61
	s_cbranch_scc0 .LBB0_710
	s_and_b64 vcc, exec, s[38:39]
	s_cbranch_vccz .LBB0_713
	s_barrier

; #define PG8_STAGE(bufoff, gbase, voff) do { _Pragma("unroll") for (int _i = 0; _i < 2; ++_i) \
;         __builtin_amdgcn_global_load_lds((const unsigned*)((const char*)(gbase) + (voff)[_i]), (PG8_LAS unsigned*)(lds + (bufoff) + ldsw + _i * 8192), 16, 0, 0); } while (0)
; #define PG8_LDA(dst, b, h) do { _Pragma("unroll") for (int m = 0; m < 4; ++m) _Pragma("unroll") for (int k = 0; k < 2; ++k) dst[m][k] = *(const PG8_LAS bf16x8*)(lds + PG8_SA(b, h) + aoff + m * 2048 + k * 1024); } while (0)
; #define PG8_LDB(dst, b, h) do { _Pragma("unroll") for (int n = 0; n < 2; ++n) _Pragma("unroll") for (int k = 0; k < 2; ++k) dst[n][k] = *(const PG8_LAS bf16x8*)(lds + PG8_SB(b, h) + boff + n * 2048 + k * 1024); } while (0)
; #define PG8_MMA(ai, bj, At, Bt) do { __builtin_amdgcn_s_setprio(1); _Pragma("unroll") for (int m = 0; m < 4; ++m) _Pragma("unroll") for (int n = 0; n < 2; ++n) _Pragma("unroll") for (int k = 0; k < 2; ++k) \
;         acc[ai][bj][m][n] = __builtin_amdgcn_mfma_f32_16x16x32_bf16(Bt[n][k], At[m][k], acc[ai][bj][m][n], 0, 0, 0); __builtin_amdgcn_s_setprio(0); } while (0)
; #define PG8_WAIT_V(n) asm volatile("s_waitcnt vmcnt(" #n ")" ::: "memory")
; #define PG8_WAIT_L(n) asm volatile("s_waitcnt lgkmcnt(" #n ")" ::: "memory")
; #define PG8_BAR __builtin_amdgcn_s_barrier()
; #define PG8_SCHED __builtin_amdgcn_sched_barrier(0)
; template <class Epi, class Sched, bool ALIGN_EPI = false, bool SP2 = false>
; __device__ __forceinline__ void gemm_phase(PG8_LAS unsigned char* lds, const Gemm g, const Sched& S, const Epi& E) {
;     ...
;             PG8_LDB(B0, 0, 0); PG8_LDB(B1, 0, 1); PG8_SCHED; PG8_LDA(At, 0, 0); PG8_STAGE(PG8_SA(1, 1), a1 + hstep, voffA);
;             PG8_WAIT_V(8); PG8_WAIT_L(0); PG8_BAR; PG8_MMA(0, 0, At, B0); PG8_MMA(0, 1, At, B1); PG8_BAR; PG8_SCHED;
;             PG8_LDA(At, 0, 1); PG8_STAGE(PG8_SB(0, 0), b2, voffB); PG8_STAGE(PG8_SB(0, 1), b2 + hstep, voffB); PG8_STAGE(PG8_SA(0, 0), a2, voffA);
;             PG8_WAIT_V(8); PG8_WAIT_L(0); PG8_BAR; PG8_MMA(1, 0, At, B0); PG8_MMA(1, 1, At, B1); PG8_BAR; PG8_SCHED;
.LBB0_881:
	ds_read_b128 v[156:159], v152
	ds_read_b128 v[160:163], v152 offset:1024
	ds_read_b128 v[164:167], v152 offset:2048
	ds_read_b128 v[168:171], v152 offset:3072
	ds_read_b128 v[172:175], v153
	ds_read_b128 v[176:179], v153 offset:1024
	ds_read_b128 v[180:183], v153 offset:2048
	ds_read_b128 v[184:187], v153 offset:3072
	s_add_u32 s46, s44, 0xfff00080
	s_addc_u32 s47, s45, -1
	s_cmp_eq_u32 s74, 60
	s_cselect_b32 s49, s37, s47
	s_cselect_b32 s48, s70, s46
	s_cselect_b32 s47, s35, s73
	s_cselect_b32 s46, s71, s72
	v_lshl_add_u64 v[146:147], s[44:45], 0, v[138:139]
	s_add_i32 m0, s43, 0xc000
	ds_read_b128 v[188:191], v154
	ds_read_b128 v[192:195], v154 offset:1024
	ds_read_b128 v[198:201], v154 offset:2048
	ds_read_b128 v[202:205], v154 offset:3072
	ds_read_b128 v[206:209], v154 offset:4096
	ds_read_b128 v[210:213], v154 offset:5120
	ds_read_b128 v[214:217], v154 offset:6144
	ds_read_b128 v[218:221], v154 offset:7168
	global_load_lds_dwordx4 v[146:147], off
	v_lshl_add_u64 v[146:147], s[44:45], 0, v[140:141]
	s_add_i32 m0, s43, 0xe000
	s_nop 0
	global_load_lds_dwordx4 v[146:147], off
	s_waitcnt vmcnt(8)
	s_waitcnt lgkmcnt(0)
	s_setprio 1
	s_barrier
	v_mfma_f32_16x16x32_bf16 v[122:125], v[156:159], v[188:191], v[122:125]
	v_mfma_f32_16x16x32_bf16 v[114:117], v[164:167], v[188:191], v[114:117]
	v_mfma_f32_16x16x32_bf16 v[106:109], v[156:159], v[198:201], v[106:109]
	v_mfma_f32_16x16x32_bf16 v[98:101], v[164:167], v[198:201], v[98:101]
	v_mfma_f32_16x16x32_bf16 v[90:93], v[156:159], v[206:209], v[90:93]
	v_mfma_f32_16x16x32_bf16 v[82:85], v[164:167], v[206:209], v[82:85]
	v_mfma_f32_16x16x32_bf16 v[74:77], v[156:159], v[214:217], v[74:77]
	v_mfma_f32_16x16x32_bf16 v[66:69], v[164:167], v[214:217], v[66:69]
	v_mfma_f32_16x16x32_bf16 v[122:125], v[160:163], v[192:195], v[122:125]
	v_mfma_f32_16x16x32_bf16 v[114:117], v[168:171], v[192:195], v[114:117]
	v_mfma_f32_16x16x32_bf16 v[106:109], v[160:163], v[202:205], v[106:109]
	v_mfma_f32_16x16x32_bf16 v[98:101], v[168:171], v[202:205], v[98:101]
	v_mfma_f32_16x16x32_bf16 v[90:93], v[160:163], v[210:213], v[90:93]
	v_mfma_f32_16x16x32_bf16 v[82:85], v[168:171], v[210:213], v[82:85]
	v_mfma_f32_16x16x32_bf16 v[74:77], v[160:163], v[218:221], v[74:77]
	v_mfma_f32_16x16x32_bf16 v[66:69], v[168:171], v[218:221], v[66:69]
	s_setprio 0
	s_setprio 1
	v_mfma_f32_16x16x32_bf16 v[126:129], v[172:175], v[188:191], v[126:129]
	v_mfma_f32_16x16x32_bf16 v[118:121], v[180:183], v[188:191], v[118:121]
	v_mfma_f32_16x16x32_bf16 v[110:113], v[172:175], v[198:201], v[110:113]
	v_mfma_f32_16x16x32_bf16 v[102:105], v[180:183], v[198:201], v[102:105]
	v_mfma_f32_16x16x32_bf16 v[94:97], v[172:175], v[206:209], v[94:97]
	v_mfma_f32_16x16x32_bf16 v[86:89], v[180:183], v[206:209], v[86:89]
	v_mfma_f32_16x16x32_bf16 v[78:81], v[172:175], v[214:217], v[78:81]
	v_mfma_f32_16x16x32_bf16 v[70:73], v[180:183], v[214:217], v[70:73]
	v_mfma_f32_16x16x32_bf16 v[126:129], v[176:179], v[192:195], v[126:129]
	v_mfma_f32_16x16x32_bf16 v[118:121], v[184:187], v[192:195], v[118:121]
	v_mfma_f32_16x16x32_bf16 v[110:113], v[176:179], v[202:205], v[110:113]
	v_mfma_f32_16x16x32_bf16 v[102:105], v[184:187], v[202:205], v[102:105]
	v_mfma_f32_16x16x32_bf16 v[94:97], v[176:179], v[210:213], v[94:97]
	v_mfma_f32_16x16x32_bf16 v[86:89], v[184:187], v[210:213], v[86:89]
	v_mfma_f32_16x16x32_bf16 v[78:81], v[176:179], v[218:221], v[78:81]
	v_mfma_f32_16x16x32_bf16 v[70:73], v[184:187], v[218:221], v[70:73]
	s_barrier
	s_setprio 0
	s_add_i32 s75, s63, s52
	v_lshl_add_u64 v[146:147], s[46:47], 0, v[134:135]
	s_mov_b32 m0, s75
	ds_read_b128 v[188:191], v154 offset:16384
	ds_read_b128 v[192:195], v154 offset:17408
	ds_read_b128 v[198:201], v154 offset:18432
	ds_read_b128 v[202:205], v154 offset:19456
	ds_read_b128 v[206:209], v154 offset:20480
	ds_read_b128 v[210:213], v154 offset:21504
	ds_read_b128 v[214:217], v154 offset:22528
	ds_read_b128 v[218:221], v154 offset:23552
	global_load_lds_dwordx4 v[146:147], off
	s_add_i32 m0, s75, 0x2000
	s_add_u32 s76, s46, 0x100000
	v_lshl_add_u64 v[222:223], s[46:47], 0, v[130:131]
	s_addc_u32 s77, s47, 0
	s_add_i32 s75, s67, s52
	global_load_lds_dwordx4 v[222:223], off
	v_lshl_add_u64 v[224:225], s[76:77], 0, v[134:135]
	s_mov_b32 m0, s75
	v_lshl_add_u64 v[226:227], s[48:49], 0, v[132:133]
	global_load_lds_dwordx4 v[224:225], off
	v_lshl_add_u64 v[224:225], s[76:77], 0, v[130:131]
	s_add_i32 m0, s75, 0x2000
	s_nop 0
	global_load_lds_dwordx4 v[224:225], off
	v_lshl_add_u64 v[224:225], s[48:49], 0, v[136:137]
	s_mov_b32 m0, s43
	s_nop 0
	global_load_lds_dwordx4 v[224:225], off
	s_mov_b32 m0, s55
	s_nop 0
	global_load_lds_dwordx4 v[226:227], off
	s_waitcnt vmcnt(8)
	s_waitcnt lgkmcnt(0)
	s_setprio 1
	s_barrier
; #define PG8_STAGE(bufoff, gbase, voff) do { _Pragma("unroll") for (int _i = 0; _i < 2; ++_i) \
;         __builtin_amdgcn_global_load_lds((const unsigned*)((const char*)(gbase) + (voff)[_i]), (PG8_LAS unsigned*)(lds + (bufoff) + ldsw + _i * 8192), 16, 0, 0); } while (0)
; #define PG8_LDA(dst, b, h) do { _Pragma("unroll") for (int m = 0; m < 4; ++m) _Pragma("unroll") for (int k = 0; k < 2; ++k) dst[m][k] = *(const PG8_LAS bf16x8*)(lds + PG8_SA(b, h) + aoff + m * 2048 + k * 1024); } while (0)
; #define PG8_LDB(dst, b, h) do { _Pragma("unroll") for (int n = 0; n < 2; ++n) _Pragma("unroll") for (int k = 0; k < 2; ++k) dst[n][k] = *(const PG8_LAS bf16x8*)(lds + PG8_SB(b, h) + boff + n * 2048 + k * 1024); } while (0)
; #define PG8_MMA(ai, bj, At, Bt) do { __builtin_amdgcn_s_setprio(1); _Pragma("unroll") for (int m = 0; m < 4; ++m) _Pragma("unroll") for (int n = 0; n < 2; ++n) _Pragma("unroll") for (int k = 0; k < 2; ++k) \
;         acc[ai][bj][m][n] = __builtin_amdgcn_mfma_f32_16x16x32_bf16(Bt[n][k], At[m][k], acc[ai][bj][m][n], 0, 0, 0); __builtin_amdgcn_s_setprio(0); } while (0)
; #define PG8_WAIT_V(n) asm volatile("s_waitcnt vmcnt(" #n ")" ::: "memory")
; #define PG8_WAIT_L(n) asm volatile("s_waitcnt lgkmcnt(" #n ")" ::: "memory")
; #define PG8_BAR __builtin_amdgcn_s_barrier()
; #define PG8_SCHED __builtin_amdgcn_sched_barrier(0)
; template <class Epi, class Sched, bool ALIGN_EPI = false, bool SP2 = false>
; __device__ __forceinline__ void gemm_phase(PG8_LAS unsigned char* lds, const Gemm g, const Sched& S, const Epi& E) {
;     ...
;             PG8_WAIT_V(8); PG8_WAIT_L(0); PG8_BAR; PG8_MMA(1, 0, At, B0); PG8_MMA(1, 1, At, B1); PG8_BAR; PG8_SCHED;
;             PG8_LDB(B0, 1, 0); PG8_LDB(B1, 1, 1); PG8_SCHED; PG8_LDA(At, 1, 0); PG8_STAGE(PG8_SA(0, 1), a2 + hstep, voffA);
;             PG8_WAIT_V(8); PG8_WAIT_L(0); PG8_BAR; PG8_MMA(0, 0, At, B0); PG8_MMA(0, 1, At, B1); PG8_BAR; PG8_SCHED;
	v_mfma_f32_16x16x32_bf16 v[58:61], v[156:159], v[188:191], v[58:61]
	v_mfma_f32_16x16x32_bf16 v[50:53], v[164:167], v[188:191], v[50:53]
	v_mfma_f32_16x16x32_bf16 v[42:45], v[156:159], v[198:201], v[42:45]
	v_mfma_f32_16x16x32_bf16 v[34:37], v[164:167], v[198:201], v[34:37]
	v_mfma_f32_16x16x32_bf16 v[26:29], v[156:159], v[206:209], v[26:29]
	v_mfma_f32_16x16x32_bf16 v[18:21], v[164:167], v[206:209], v[18:21]
	v_mfma_f32_16x16x32_bf16 v[10:13], v[156:159], v[214:217], v[10:13]
	v_mfma_f32_16x16x32_bf16 v[6:9], v[164:167], v[214:217], v[6:9]
	v_mfma_f32_16x16x32_bf16 v[58:61], v[160:163], v[192:195], v[58:61]
	v_mfma_f32_16x16x32_bf16 v[50:53], v[168:171], v[192:195], v[50:53]
	v_mfma_f32_16x16x32_bf16 v[42:45], v[160:163], v[202:205], v[42:45]
	v_mfma_f32_16x16x32_bf16 v[34:37], v[168:171], v[202:205], v[34:37]
	v_mfma_f32_16x16x32_bf16 v[26:29], v[160:163], v[210:213], v[26:29]
	v_mfma_f32_16x16x32_bf16 v[18:21], v[168:171], v[210:213], v[18:21]
	v_mfma_f32_16x16x32_bf16 v[10:13], v[160:163], v[218:221], v[10:13]
	v_mfma_f32_16x16x32_bf16 v[6:9], v[168:171], v[218:221], v[6:9]
	s_setprio 0
	s_setprio 1
	v_mfma_f32_16x16x32_bf16 v[62:65], v[172:175], v[188:191], v[62:65]
	v_mfma_f32_16x16x32_bf16 v[54:57], v[180:183], v[188:191], v[54:57]
	v_mfma_f32_16x16x32_bf16 v[46:49], v[172:175], v[198:201], v[46:49]
	v_mfma_f32_16x16x32_bf16 v[38:41], v[180:183], v[198:201], v[38:41]
	v_mfma_f32_16x16x32_bf16 v[30:33], v[172:175], v[206:209], v[30:33]
	v_mfma_f32_16x16x32_bf16 v[22:25], v[180:183], v[206:209], v[22:25]
	v_mfma_f32_16x16x32_bf16 v[14:17], v[172:175], v[214:217], v[14:17]
	v_mfma_f32_16x16x32_bf16 v[2:5], v[180:183], v[214:217], v[2:5]
	v_mfma_f32_16x16x32_bf16 v[62:65], v[176:179], v[192:195], v[62:65]
	v_mfma_f32_16x16x32_bf16 v[54:57], v[184:187], v[192:195], v[54:57]
	v_mfma_f32_16x16x32_bf16 v[46:49], v[176:179], v[202:205], v[46:49]
	v_mfma_f32_16x16x32_bf16 v[38:41], v[184:187], v[202:205], v[38:41]
	v_mfma_f32_16x16x32_bf16 v[30:33], v[176:179], v[210:213], v[30:33]
	v_mfma_f32_16x16x32_bf16 v[22:25], v[184:187], v[210:213], v[22:25]
	v_mfma_f32_16x16x32_bf16 v[14:17], v[176:179], v[218:221], v[14:17]
	v_mfma_f32_16x16x32_bf16 v[2:5], v[184:187], v[218:221], v[2:5]
	s_barrier
	s_setprio 0
	s_add_i32 s75, 0, 0x18000
	v_add_u32_e32 v155, s75, v150
	s_add_i32 s76, 0, 0x1c000
	ds_read_b128 v[156:159], v155
	ds_read_b128 v[160:163], v155 offset:1024
	ds_read_b128 v[164:167], v155 offset:2048
	ds_read_b128 v[168:171], v155 offset:3072
	v_add_u32_e32 v155, s76, v150
	ds_read_b128 v[172:175], v155
	ds_read_b128 v[176:179], v155 offset:1024
	ds_read_b128 v[180:183], v155 offset:2048
	ds_read_b128 v[184:187], v155 offset:3072
	s_add_u32 s48, s48, 0x100000
	s_addc_u32 s49, s49, 0
	s_mov_b32 m0, s56
	v_lshl_add_u64 v[228:229], s[48:49], 0, v[136:137]
	ds_read_b128 v[188:191], v154 offset:32768
	ds_read_b128 v[192:195], v154 offset:33792
	ds_read_b128 v[198:201], v154 offset:34816
	ds_read_b128 v[202:205], v154 offset:35840
	ds_read_b128 v[206:209], v154 offset:36864
	ds_read_b128 v[210:213], v154 offset:37888
	ds_read_b128 v[214:217], v154 offset:38912
	ds_read_b128 v[218:221], v154 offset:39936
	global_load_lds_dwordx4 v[228:229], off
	v_lshl_add_u64 v[228:229], s[48:49], 0, v[132:133]
	s_mov_b32 m0, s57
	s_nop 0
	global_load_lds_dwordx4 v[228:229], off
	s_waitcnt vmcnt(8)
	s_waitcnt lgkmcnt(0)
	s_setprio 1
	s_barrier
	v_mfma_f32_16x16x32_bf16 v[122:125], v[156:159], v[188:191], v[122:125]
	v_mfma_f32_16x16x32_bf16 v[114:117], v[164:167], v[188:191], v[114:117]
	v_mfma_f32_16x16x32_bf16 v[106:109], v[156:159], v[198:201], v[106:109]
	v_mfma_f32_16x16x32_bf16 v[98:101], v[164:167], v[198:201], v[98:101]
	v_mfma_f32_16x16x32_bf16 v[90:93], v[156:159], v[206:209], v[90:93]
	v_mfma_f32_16x16x32_bf16 v[82:85], v[164:167], v[206:209], v[82:85]
	v_mfma_f32_16x16x32_bf16 v[74:77], v[156:159], v[214:217], v[74:77]
	v_mfma_f32_16x16x32_bf16 v[66:69], v[164:167], v[214:217], v[66:69]
	v_mfma_f32_16x16x32_bf16 v[122:125], v[160:163], v[192:195], v[122:125]
	v_mfma_f32_16x16x32_bf16 v[114:117], v[168:171], v[192:195], v[114:117]
	v_mfma_f32_16x16x32_bf16 v[106:109], v[160:163], v[202:205], v[106:109]
	v_mfma_f32_16x16x32_bf16 v[98:101], v[168:171], v[202:205], v[98:101]
	v_mfma_f32_16x16x32_bf16 v[90:93], v[160:163], v[210:213], v[90:93]
	v_mfma_f32_16x16x32_bf16 v[82:85], v[168:171], v[210:213], v[82:85]
	v_mfma_f32_16x16x32_bf16 v[74:77], v[160:163], v[218:221], v[74:77]
	v_mfma_f32_16x16x32_bf16 v[66:69], v[168:171], v[218:221], v[66:69]
	s_setprio 0
	s_setprio 1
	v_mfma_f32_16x16x32_bf16 v[126:129], v[172:175], v[188:191], v[126:129]
	v_mfma_f32_16x16x32_bf16 v[118:121], v[180:183], v[188:191], v[118:121]
	v_mfma_f32_16x16x32_bf16 v[110:113], v[172:175], v[198:201], v[110:113]
	v_mfma_f32_16x16x32_bf16 v[102:105], v[180:183], v[198:201], v[102:105]
	v_mfma_f32_16x16x32_bf16 v[94:97], v[172:175], v[206:209], v[94:97]
	v_mfma_f32_16x16x32_bf16 v[86:89], v[180:183], v[206:209], v[86:89]
	v_mfma_f32_16x16x32_bf16 v[78:81], v[172:175], v[214:217], v[78:81]
	v_mfma_f32_16x16x32_bf16 v[70:73], v[180:183], v[214:217], v[70:73]
	v_mfma_f32_16x16x32_bf16 v[126:129], v[176:179], v[192:195], v[126:129]
	v_mfma_f32_16x16x32_bf16 v[118:121], v[184:187], v[192:195], v[118:121]
	v_mfma_f32_16x16x32_bf16 v[110:113], v[176:179], v[202:205], v[110:113]
	v_mfma_f32_16x16x32_bf16 v[102:105], v[184:187], v[202:205], v[102:105]
	v_mfma_f32_16x16x32_bf16 v[94:97], v[176:179], v[210:213], v[94:97]
	v_mfma_f32_16x16x32_bf16 v[86:89], v[184:187], v[210:213], v[86:89]
	v_mfma_f32_16x16x32_bf16 v[78:81], v[176:179], v[218:221], v[78:81]
	v_mfma_f32_16x16x32_bf16 v[70:73], v[184:187], v[218:221], v[70:73]
	s_barrier
; #define PG8_STAGE(bufoff, gbase, voff) do { _Pragma("unroll") for (int _i = 0; _i < 2; ++_i) \
;         __builtin_amdgcn_global_load_lds((const unsigned*)((const char*)(gbase) + (voff)[_i]), (PG8_LAS unsigned*)(lds + (bufoff) + ldsw + _i * 8192), 16, 0, 0); } while (0)
; #define PG8_LDA(dst, b, h) do { _Pragma("unroll") for (int m = 0; m < 4; ++m) _Pragma("unroll") for (int k = 0; k < 2; ++k) dst[m][k] = *(const PG8_LAS bf16x8*)(lds + PG8_SA(b, h) + aoff + m * 2048 + k * 1024); } while (0)
; #define PG8_MMA(ai, bj, At, Bt) do { __builtin_amdgcn_s_setprio(1); _Pragma("unroll") for (int m = 0; m < 4; ++m) _Pragma("unroll") for (int n = 0; n < 2; ++n) _Pragma("unroll") for (int k = 0; k < 2; ++k) \
;         acc[ai][bj][m][n] = __builtin_amdgcn_mfma_f32_16x16x32_bf16(Bt[n][k], At[m][k], acc[ai][bj][m][n], 0, 0, 0); __builtin_amdgcn_s_setprio(0); } while (0)
; #define PG8_WAIT_V(n) asm volatile("s_waitcnt vmcnt(" #n ")" ::: "memory")
; #define PG8_WAIT_L(n) asm volatile("s_waitcnt lgkmcnt(" #n ")" ::: "memory")
; #define PG8_BAR __builtin_amdgcn_s_barrier()
; #define PG8_SCHED __builtin_amdgcn_sched_barrier(0)
; template <class Epi, class Sched, bool ALIGN_EPI = false, bool SP2 = false>
; __device__ __forceinline__ void gemm_phase(PG8_LAS unsigned char* lds, const Gemm g, const Sched& S, const Epi& E) {
;     ...
;             PG8_LDA(At, 1, 1); PG8_STAGE(PG8_SB(1, 0), b3, voffB); PG8_STAGE(PG8_SB(1, 1), b3 + hstep, voffB); PG8_STAGE(PG8_SA(1, 0), a3, voffA);
;             PG8_WAIT_V(8); PG8_WAIT_L(0); PG8_BAR; PG8_MMA(1, 0, At, B0); PG8_MMA(1, 1, At, B1); PG8_BAR; PG8_SCHED;
;     ...
;         if constexpr (ALIGN_EPI) { if (wr == 0) PG8_BAR; }
	s_setprio 0
	s_add_i32 s48, s75, s52
	v_lshl_add_u64 v[146:147], v[146:147], 0, s[12:13]
	s_mov_b32 m0, s48
	ds_read_b128 v[188:191], v154 offset:49152
	ds_read_b128 v[192:195], v154 offset:50176
	ds_read_b128 v[198:201], v154 offset:51200
	ds_read_b128 v[202:205], v154 offset:52224
	ds_read_b128 v[206:209], v154 offset:53248
	ds_read_b128 v[210:213], v154 offset:54272
	ds_read_b128 v[214:217], v154 offset:55296
	ds_read_b128 v[218:221], v154 offset:56320
	global_load_lds_dwordx4 v[146:147], off
	s_add_i32 m0, s48, 0x2000
	s_add_u32 s46, s46, 0x100080
	v_lshl_add_u64 v[146:147], v[222:223], 0, s[12:13]
	s_addc_u32 s47, s47, 0
	s_add_i32 s48, s76, s52
	global_load_lds_dwordx4 v[146:147], off
	v_lshl_add_u64 v[146:147], s[46:47], 0, v[134:135]
	s_mov_b32 m0, s48
	s_nop 0
	global_load_lds_dwordx4 v[146:147], off
	v_lshl_add_u64 v[146:147], s[46:47], 0, v[130:131]
	s_add_i32 m0, s48, 0x2000
	s_nop 0
	global_load_lds_dwordx4 v[146:147], off
	v_lshl_add_u64 v[146:147], v[224:225], 0, s[12:13]
	s_mov_b32 m0, s59
	s_nop 0
	global_load_lds_dwordx4 v[146:147], off
	v_lshl_add_u64 v[146:147], v[226:227], 0, s[12:13]
	s_mov_b32 m0, s60
	s_nop 0
	global_load_lds_dwordx4 v[146:147], off
	s_waitcnt vmcnt(8)
	s_waitcnt lgkmcnt(0)
	s_setprio 1
	s_barrier
	v_mfma_f32_16x16x32_bf16 v[58:61], v[156:159], v[188:191], v[58:61]
	v_mfma_f32_16x16x32_bf16 v[50:53], v[164:167], v[188:191], v[50:53]
	v_mfma_f32_16x16x32_bf16 v[42:45], v[156:159], v[198:201], v[42:45]
	v_mfma_f32_16x16x32_bf16 v[34:37], v[164:167], v[198:201], v[34:37]
	v_mfma_f32_16x16x32_bf16 v[26:29], v[156:159], v[206:209], v[26:29]
	v_mfma_f32_16x16x32_bf16 v[18:21], v[164:167], v[206:209], v[18:21]
	v_mfma_f32_16x16x32_bf16 v[10:13], v[156:159], v[214:217], v[10:13]
	v_mfma_f32_16x16x32_bf16 v[6:9], v[164:167], v[214:217], v[6:9]
	v_mfma_f32_16x16x32_bf16 v[58:61], v[160:163], v[192:195], v[58:61]
	v_mfma_f32_16x16x32_bf16 v[50:53], v[168:171], v[192:195], v[50:53]
	v_mfma_f32_16x16x32_bf16 v[42:45], v[160:163], v[202:205], v[42:45]
	v_mfma_f32_16x16x32_bf16 v[34:37], v[168:171], v[202:205], v[34:37]
	v_mfma_f32_16x16x32_bf16 v[26:29], v[160:163], v[210:213], v[26:29]
	v_mfma_f32_16x16x32_bf16 v[18:21], v[168:171], v[210:213], v[18:21]
	v_mfma_f32_16x16x32_bf16 v[10:13], v[160:163], v[218:221], v[10:13]
	v_mfma_f32_16x16x32_bf16 v[6:9], v[168:171], v[218:221], v[6:9]
	s_setprio 0
	s_setprio 1
	v_mfma_f32_16x16x32_bf16 v[62:65], v[172:175], v[188:191], v[62:65]
	v_mfma_f32_16x16x32_bf16 v[54:57], v[180:183], v[188:191], v[54:57]
	v_mfma_f32_16x16x32_bf16 v[46:49], v[172:175], v[198:201], v[46:49]
	v_mfma_f32_16x16x32_bf16 v[38:41], v[180:183], v[198:201], v[38:41]
	v_mfma_f32_16x16x32_bf16 v[30:33], v[172:175], v[206:209], v[30:33]
	v_mfma_f32_16x16x32_bf16 v[22:25], v[180:183], v[206:209], v[22:25]
	v_mfma_f32_16x16x32_bf16 v[14:17], v[172:175], v[214:217], v[14:17]
	v_mfma_f32_16x16x32_bf16 v[2:5], v[180:183], v[214:217], v[2:5]
	v_mfma_f32_16x16x32_bf16 v[62:65], v[176:179], v[192:195], v[62:65]
	v_mfma_f32_16x16x32_bf16 v[54:57], v[184:187], v[192:195], v[54:57]
	v_mfma_f32_16x16x32_bf16 v[46:49], v[176:179], v[202:205], v[46:49]
	v_mfma_f32_16x16x32_bf16 v[38:41], v[184:187], v[202:205], v[38:41]
	v_mfma_f32_16x16x32_bf16 v[30:33], v[176:179], v[210:213], v[30:33]
	v_mfma_f32_16x16x32_bf16 v[22:25], v[184:187], v[210:213], v[22:25]
	v_mfma_f32_16x16x32_bf16 v[14:17], v[176:179], v[218:221], v[14:17]
	v_mfma_f32_16x16x32_bf16 v[2:5], v[184:187], v[218:221], v[2:5]
	s_barrier
	s_setprio 0
	s_add_i32 s74, s74, 2
	s_add_u32 s44, s44, 0x100
	s_addc_u32 s45, s45, 0
	s_add_u32 s72, s72, 0x100
	s_addc_u32 s73, s73, 0
	s_cmp_gt_u32 s74, 61
	s_cbranch_scc0 .LBB0_881
	s_and_b64 vcc, exec, s[16:17]
	s_cbranch_vccz .LBB0_884
	s_barrier

; #define PG8_STAGE(bufoff, gbase, voff) do { _Pragma("unroll") for (int _i = 0; _i < 2; ++_i) \
;         __builtin_amdgcn_global_load_lds((const unsigned*)((const char*)(gbase) + (voff)[_i]), (PG8_LAS unsigned*)(lds + (bufoff) + ldsw + _i * 8192), 16, 0, 0); } while (0)
; #define PG8_LDA(dst, b, h) do { _Pragma("unroll") for (int m = 0; m < 4; ++m) _Pragma("unroll") for (int k = 0; k < 2; ++k) dst[m][k] = *(const PG8_LAS bf16x8*)(lds + PG8_SA(b, h) + aoff + m * 2048 + k * 1024); } while (0)
; #define PG8_LDB(dst, b, h) do { _Pragma("unroll") for (int n = 0; n < 2; ++n) _Pragma("unroll") for (int k = 0; k < 2; ++k) dst[n][k] = *(const PG8_LAS bf16x8*)(lds + PG8_SB(b, h) + boff + n * 2048 + k * 1024); } while (0)
; #define PG8_MMA(ai, bj, At, Bt) do { __builtin_amdgcn_s_setprio(1); _Pragma("unroll") for (int m = 0; m < 4; ++m) _Pragma("unroll") for (int n = 0; n < 2; ++n) _Pragma("unroll") for (int k = 0; k < 2; ++k) \
;         acc[ai][bj][m][n] = __builtin_amdgcn_mfma_f32_16x16x32_bf16(Bt[n][k], At[m][k], acc[ai][bj][m][n], 0, 0, 0); __builtin_amdgcn_s_setprio(0); } while (0)
; #define PG8_WAIT_V(n) asm volatile("s_waitcnt vmcnt(" #n ")" ::: "memory")
; #define PG8_WAIT_L(n) asm volatile("s_waitcnt lgkmcnt(" #n ")" ::: "memory")
; #define PG8_BAR __builtin_amdgcn_s_barrier()
; #define PG8_SCHED __builtin_amdgcn_sched_barrier(0)
; template <class Epi, class Sched, bool ALIGN_EPI = false, bool SP2 = false>
; __device__ __forceinline__ void gemm_phase(PG8_LAS unsigned char* lds, const Gemm g, const Sched& S, const Epi& E) {
;     ...
;             PG8_LDB(B0, 0, 0); PG8_LDB(B1, 0, 1); PG8_SCHED; PG8_LDA(At, 0, 0); PG8_STAGE(PG8_SA(1, 1), a1 + hstep, voffA);
;             PG8_WAIT_V(8); PG8_WAIT_L(0); PG8_BAR; PG8_MMA(0, 0, At, B0); PG8_MMA(0, 1, At, B1); PG8_BAR; PG8_SCHED;
;             PG8_LDA(At, 0, 1); PG8_STAGE(PG8_SB(0, 0), b2, voffB); PG8_STAGE(PG8_SB(0, 1), b2 + hstep, voffB); PG8_STAGE(PG8_SA(0, 0), a2, voffA);
;             PG8_WAIT_V(8); PG8_WAIT_L(0); PG8_BAR; PG8_MMA(1, 0, At, B0); PG8_MMA(1, 1, At, B1); PG8_BAR; PG8_SCHED;
.LBB0_984:
	ds_read_b128 v[146:149], v160
	ds_read_b128 v[164:167], v160 offset:1024
	ds_read_b128 v[168:171], v160 offset:2048
	ds_read_b128 v[172:175], v160 offset:3072
	ds_read_b128 v[176:179], v161
	ds_read_b128 v[180:183], v161 offset:1024
	ds_read_b128 v[184:187], v161 offset:2048
	ds_read_b128 v[188:191], v161 offset:3072
	s_add_u32 s44, s42, 0xffd50080
	s_addc_u32 s45, s43, -1
	s_cmpk_eq_i32 s71, 0xa8
	s_cselect_b32 s47, s7, s45
	s_cselect_b32 s46, s6, s44
	s_cselect_b32 s45, s41, s70
	s_cselect_b32 s44, s40, s69
	v_lshl_add_u64 v[226:227], s[42:43], 0, v[138:139]
	s_add_i32 m0, s52, 0xc000
	ds_read_b128 v[192:195], v162
	ds_read_b128 v[198:201], v162 offset:1024
	ds_read_b128 v[202:205], v162 offset:2048
	ds_read_b128 v[206:209], v162 offset:3072
	ds_read_b128 v[210:213], v162 offset:4096
	ds_read_b128 v[214:217], v162 offset:5120
	ds_read_b128 v[218:221], v162 offset:6144
	ds_read_b128 v[222:225], v162 offset:7168
	global_load_lds_dwordx4 v[226:227], off
	v_lshl_add_u64 v[226:227], s[42:43], 0, v[140:141]
	s_add_i32 m0, s52, 0xe000
	s_nop 0
	global_load_lds_dwordx4 v[226:227], off
	s_waitcnt vmcnt(8)
	s_waitcnt lgkmcnt(0)
	s_setprio 1
	s_barrier
	v_mfma_f32_16x16x32_bf16 v[126:129], v[146:149], v[192:195], v[126:129]
	v_mfma_f32_16x16x32_bf16 v[122:125], v[168:171], v[192:195], v[122:125]
	v_mfma_f32_16x16x32_bf16 v[110:113], v[146:149], v[202:205], v[110:113]
	v_mfma_f32_16x16x32_bf16 v[106:109], v[168:171], v[202:205], v[106:109]
	v_mfma_f32_16x16x32_bf16 v[94:97], v[146:149], v[210:213], v[94:97]
	v_mfma_f32_16x16x32_bf16 v[90:93], v[168:171], v[210:213], v[90:93]
	v_mfma_f32_16x16x32_bf16 v[78:81], v[146:149], v[218:221], v[78:81]
	v_mfma_f32_16x16x32_bf16 v[74:77], v[168:171], v[218:221], v[74:77]
	v_mfma_f32_16x16x32_bf16 v[126:129], v[164:167], v[198:201], v[126:129]
	v_mfma_f32_16x16x32_bf16 v[122:125], v[172:175], v[198:201], v[122:125]
	v_mfma_f32_16x16x32_bf16 v[110:113], v[164:167], v[206:209], v[110:113]
	v_mfma_f32_16x16x32_bf16 v[106:109], v[172:175], v[206:209], v[106:109]
	v_mfma_f32_16x16x32_bf16 v[94:97], v[164:167], v[214:217], v[94:97]
	v_mfma_f32_16x16x32_bf16 v[90:93], v[172:175], v[214:217], v[90:93]
	v_mfma_f32_16x16x32_bf16 v[78:81], v[164:167], v[222:225], v[78:81]
	v_mfma_f32_16x16x32_bf16 v[74:77], v[172:175], v[222:225], v[74:77]
	s_setprio 0
	s_setprio 1
	v_mfma_f32_16x16x32_bf16 v[118:121], v[176:179], v[192:195], v[118:121]
	v_mfma_f32_16x16x32_bf16 v[114:117], v[184:187], v[192:195], v[114:117]
	v_mfma_f32_16x16x32_bf16 v[102:105], v[176:179], v[202:205], v[102:105]
	v_mfma_f32_16x16x32_bf16 v[98:101], v[184:187], v[202:205], v[98:101]
	v_mfma_f32_16x16x32_bf16 v[86:89], v[176:179], v[210:213], v[86:89]
	v_mfma_f32_16x16x32_bf16 v[82:85], v[184:187], v[210:213], v[82:85]
	v_mfma_f32_16x16x32_bf16 v[70:73], v[176:179], v[218:221], v[70:73]
	v_mfma_f32_16x16x32_bf16 v[66:69], v[184:187], v[218:221], v[66:69]
	v_mfma_f32_16x16x32_bf16 v[118:121], v[180:183], v[198:201], v[118:121]
	v_mfma_f32_16x16x32_bf16 v[114:117], v[188:191], v[198:201], v[114:117]
	v_mfma_f32_16x16x32_bf16 v[102:105], v[180:183], v[206:209], v[102:105]
	v_mfma_f32_16x16x32_bf16 v[98:101], v[188:191], v[206:209], v[98:101]
	v_mfma_f32_16x16x32_bf16 v[86:89], v[180:183], v[214:217], v[86:89]
	v_mfma_f32_16x16x32_bf16 v[82:85], v[188:191], v[214:217], v[82:85]
	v_mfma_f32_16x16x32_bf16 v[70:73], v[180:183], v[222:225], v[70:73]
	v_mfma_f32_16x16x32_bf16 v[66:69], v[188:191], v[222:225], v[66:69]
	s_barrier
	s_setprio 0
	s_add_i32 s72, s62, s51
	v_lshl_add_u64 v[226:227], s[44:45], 0, v[132:133]
	s_mov_b32 m0, s72
	ds_read_b128 v[192:195], v162 offset:16384
	ds_read_b128 v[198:201], v162 offset:17408
	ds_read_b128 v[202:205], v162 offset:18432
	ds_read_b128 v[206:209], v162 offset:19456
	ds_read_b128 v[210:213], v162 offset:20480
	ds_read_b128 v[214:217], v162 offset:21504
	ds_read_b128 v[218:221], v162 offset:22528
	ds_read_b128 v[222:225], v162 offset:23552
	global_load_lds_dwordx4 v[226:227], off
	s_add_i32 m0, s72, 0x2000
	s_add_u32 s72, s44, 0x2b0000
	v_lshl_add_u64 v[228:229], s[44:45], 0, v[136:137]
	s_addc_u32 s73, s45, 0
	s_add_i32 s74, s63, s51
	global_load_lds_dwordx4 v[228:229], off
	v_lshl_add_u64 v[230:231], s[72:73], 0, v[132:133]
	s_mov_b32 m0, s74
	v_lshl_add_u64 v[232:233], s[46:47], 0, v[134:135]
	global_load_lds_dwordx4 v[230:231], off
	v_lshl_add_u64 v[230:231], s[72:73], 0, v[136:137]
	s_add_i32 m0, s74, 0x2000
	s_nop 0
	global_load_lds_dwordx4 v[230:231], off
	v_lshl_add_u64 v[230:231], s[46:47], 0, v[130:131]
	s_mov_b32 m0, s52
	s_nop 0
	global_load_lds_dwordx4 v[230:231], off
	s_mov_b32 m0, s53
	s_nop 0
	global_load_lds_dwordx4 v[232:233], off
	s_waitcnt vmcnt(8)
	s_waitcnt lgkmcnt(0)
	s_setprio 1
	s_barrier
; #define PG8_STAGE(bufoff, gbase, voff) do { _Pragma("unroll") for (int _i = 0; _i < 2; ++_i) \
;         __builtin_amdgcn_global_load_lds((const unsigned*)((const char*)(gbase) + (voff)[_i]), (PG8_LAS unsigned*)(lds + (bufoff) + ldsw + _i * 8192), 16, 0, 0); } while (0)
; #define PG8_LDA(dst, b, h) do { _Pragma("unroll") for (int m = 0; m < 4; ++m) _Pragma("unroll") for (int k = 0; k < 2; ++k) dst[m][k] = *(const PG8_LAS bf16x8*)(lds + PG8_SA(b, h) + aoff + m * 2048 + k * 1024); } while (0)
; #define PG8_LDB(dst, b, h) do { _Pragma("unroll") for (int n = 0; n < 2; ++n) _Pragma("unroll") for (int k = 0; k < 2; ++k) dst[n][k] = *(const PG8_LAS bf16x8*)(lds + PG8_SB(b, h) + boff + n * 2048 + k * 1024); } while (0)
; #define PG8_MMA(ai, bj, At, Bt) do { __builtin_amdgcn_s_setprio(1); _Pragma("unroll") for (int m = 0; m < 4; ++m) _Pragma("unroll") for (int n = 0; n < 2; ++n) _Pragma("unroll") for (int k = 0; k < 2; ++k) \
;         acc[ai][bj][m][n] = __builtin_amdgcn_mfma_f32_16x16x32_bf16(Bt[n][k], At[m][k], acc[ai][bj][m][n], 0, 0, 0); __builtin_amdgcn_s_setprio(0); } while (0)
; #define PG8_WAIT_V(n) asm volatile("s_waitcnt vmcnt(" #n ")" ::: "memory")
; #define PG8_WAIT_L(n) asm volatile("s_waitcnt lgkmcnt(" #n ")" ::: "memory")
; #define PG8_BAR __builtin_amdgcn_s_barrier()
; #define PG8_SCHED __builtin_amdgcn_sched_barrier(0)
; template <class Epi, class Sched, bool ALIGN_EPI = false, bool SP2 = false>
; __device__ __forceinline__ void gemm_phase(PG8_LAS unsigned char* lds, const Gemm g, const Sched& S, const Epi& E) {
;     ...
;             PG8_WAIT_V(8); PG8_WAIT_L(0); PG8_BAR; PG8_MMA(1, 0, At, B0); PG8_MMA(1, 1, At, B1); PG8_BAR; PG8_SCHED;
;             PG8_LDB(B0, 1, 0); PG8_LDB(B1, 1, 1); PG8_SCHED; PG8_LDA(At, 1, 0); PG8_STAGE(PG8_SA(0, 1), a2 + hstep, voffA);
;             PG8_WAIT_V(8); PG8_WAIT_L(0); PG8_BAR; PG8_MMA(0, 0, At, B0); PG8_MMA(0, 1, At, B1); PG8_BAR; PG8_SCHED;
	v_mfma_f32_16x16x32_bf16 v[62:65], v[146:149], v[192:195], v[62:65]
	v_mfma_f32_16x16x32_bf16 v[58:61], v[168:171], v[192:195], v[58:61]
	v_mfma_f32_16x16x32_bf16 v[46:49], v[146:149], v[202:205], v[46:49]
	v_mfma_f32_16x16x32_bf16 v[42:45], v[168:171], v[202:205], v[42:45]
	v_mfma_f32_16x16x32_bf16 v[30:33], v[146:149], v[210:213], v[30:33]
	v_mfma_f32_16x16x32_bf16 v[26:29], v[168:171], v[210:213], v[26:29]
	v_mfma_f32_16x16x32_bf16 v[14:17], v[146:149], v[218:221], v[14:17]
	v_mfma_f32_16x16x32_bf16 v[10:13], v[168:171], v[218:221], v[10:13]
	v_mfma_f32_16x16x32_bf16 v[62:65], v[164:167], v[198:201], v[62:65]
	v_mfma_f32_16x16x32_bf16 v[58:61], v[172:175], v[198:201], v[58:61]
	v_mfma_f32_16x16x32_bf16 v[46:49], v[164:167], v[206:209], v[46:49]
	v_mfma_f32_16x16x32_bf16 v[42:45], v[172:175], v[206:209], v[42:45]
	v_mfma_f32_16x16x32_bf16 v[30:33], v[164:167], v[214:217], v[30:33]
	v_mfma_f32_16x16x32_bf16 v[26:29], v[172:175], v[214:217], v[26:29]
	v_mfma_f32_16x16x32_bf16 v[14:17], v[164:167], v[222:225], v[14:17]
	v_mfma_f32_16x16x32_bf16 v[10:13], v[172:175], v[222:225], v[10:13]
	s_setprio 0
	s_setprio 1
	v_mfma_f32_16x16x32_bf16 v[54:57], v[176:179], v[192:195], v[54:57]
	v_mfma_f32_16x16x32_bf16 v[50:53], v[184:187], v[192:195], v[50:53]
	v_mfma_f32_16x16x32_bf16 v[38:41], v[176:179], v[202:205], v[38:41]
	v_mfma_f32_16x16x32_bf16 v[34:37], v[184:187], v[202:205], v[34:37]
	v_mfma_f32_16x16x32_bf16 v[22:25], v[176:179], v[210:213], v[22:25]
	v_mfma_f32_16x16x32_bf16 v[18:21], v[184:187], v[210:213], v[18:21]
	v_mfma_f32_16x16x32_bf16 v[6:9], v[176:179], v[218:221], v[6:9]
	v_mfma_f32_16x16x32_bf16 v[2:5], v[184:187], v[218:221], v[2:5]
	v_mfma_f32_16x16x32_bf16 v[54:57], v[180:183], v[198:201], v[54:57]
	v_mfma_f32_16x16x32_bf16 v[50:53], v[188:191], v[198:201], v[50:53]
	v_mfma_f32_16x16x32_bf16 v[38:41], v[180:183], v[206:209], v[38:41]
	v_mfma_f32_16x16x32_bf16 v[34:37], v[188:191], v[206:209], v[34:37]
	v_mfma_f32_16x16x32_bf16 v[22:25], v[180:183], v[214:217], v[22:25]
	v_mfma_f32_16x16x32_bf16 v[18:21], v[188:191], v[214:217], v[18:21]
	v_mfma_f32_16x16x32_bf16 v[6:9], v[180:183], v[222:225], v[6:9]
	v_mfma_f32_16x16x32_bf16 v[2:5], v[188:191], v[222:225], v[2:5]
	s_barrier
	s_setprio 0
	s_add_i32 s72, 0, 0x18000
	s_add_i32 s73, 0, 0x1c000
	v_add_u32_e32 v172, s72, v151
	v_add_u32_e32 v188, s73, v151
	ds_read_b128 v[146:149], v172
	ds_read_b128 v[164:167], v172 offset:1024
	ds_read_b128 v[168:171], v172 offset:2048
	ds_read_b128 v[172:175], v172 offset:3072
	ds_read_b128 v[176:179], v188
	ds_read_b128 v[180:183], v188 offset:1024
	ds_read_b128 v[184:187], v188 offset:2048
	ds_read_b128 v[188:191], v188 offset:3072
	s_add_u32 s46, s46, 0x2b0000
	s_addc_u32 s47, s47, 0
	s_mov_b32 m0, s54
	v_lshl_add_u64 v[234:235], s[46:47], 0, v[130:131]
	ds_read_b128 v[192:195], v162 offset:32768
	ds_read_b128 v[198:201], v162 offset:33792
	ds_read_b128 v[202:205], v162 offset:34816
	ds_read_b128 v[206:209], v162 offset:35840
	ds_read_b128 v[210:213], v162 offset:36864
	ds_read_b128 v[214:217], v162 offset:37888
	ds_read_b128 v[218:221], v162 offset:38912
	ds_read_b128 v[222:225], v162 offset:39936
	global_load_lds_dwordx4 v[234:235], off
	v_lshl_add_u64 v[234:235], s[46:47], 0, v[134:135]
	s_mov_b32 m0, s55
	s_nop 0
	global_load_lds_dwordx4 v[234:235], off
	s_waitcnt vmcnt(8)
	s_waitcnt lgkmcnt(0)
	s_setprio 1
	s_barrier
	v_mfma_f32_16x16x32_bf16 v[126:129], v[146:149], v[192:195], v[126:129]
	v_mfma_f32_16x16x32_bf16 v[122:125], v[168:171], v[192:195], v[122:125]
	v_mfma_f32_16x16x32_bf16 v[110:113], v[146:149], v[202:205], v[110:113]
	v_mfma_f32_16x16x32_bf16 v[106:109], v[168:171], v[202:205], v[106:109]
	v_mfma_f32_16x16x32_bf16 v[94:97], v[146:149], v[210:213], v[94:97]
	v_mfma_f32_16x16x32_bf16 v[90:93], v[168:171], v[210:213], v[90:93]
	v_mfma_f32_16x16x32_bf16 v[78:81], v[146:149], v[218:221], v[78:81]
	v_mfma_f32_16x16x32_bf16 v[74:77], v[168:171], v[218:221], v[74:77]
	v_mfma_f32_16x16x32_bf16 v[126:129], v[164:167], v[198:201], v[126:129]
	v_mfma_f32_16x16x32_bf16 v[122:125], v[172:175], v[198:201], v[122:125]
	v_mfma_f32_16x16x32_bf16 v[110:113], v[164:167], v[206:209], v[110:113]
	v_mfma_f32_16x16x32_bf16 v[106:109], v[172:175], v[206:209], v[106:109]
	v_mfma_f32_16x16x32_bf16 v[94:97], v[164:167], v[214:217], v[94:97]
	v_mfma_f32_16x16x32_bf16 v[90:93], v[172:175], v[214:217], v[90:93]
	v_mfma_f32_16x16x32_bf16 v[78:81], v[164:167], v[222:225], v[78:81]
	v_mfma_f32_16x16x32_bf16 v[74:77], v[172:175], v[222:225], v[74:77]
	s_setprio 0
	s_setprio 1
	v_mfma_f32_16x16x32_bf16 v[118:121], v[176:179], v[192:195], v[118:121]
	v_mfma_f32_16x16x32_bf16 v[114:117], v[184:187], v[192:195], v[114:117]
	v_mfma_f32_16x16x32_bf16 v[102:105], v[176:179], v[202:205], v[102:105]
	v_mfma_f32_16x16x32_bf16 v[98:101], v[184:187], v[202:205], v[98:101]
	v_mfma_f32_16x16x32_bf16 v[86:89], v[176:179], v[210:213], v[86:89]
	v_mfma_f32_16x16x32_bf16 v[82:85], v[184:187], v[210:213], v[82:85]
	v_mfma_f32_16x16x32_bf16 v[70:73], v[176:179], v[218:221], v[70:73]
	v_mfma_f32_16x16x32_bf16 v[66:69], v[184:187], v[218:221], v[66:69]
	v_mfma_f32_16x16x32_bf16 v[118:121], v[180:183], v[198:201], v[118:121]
	v_mfma_f32_16x16x32_bf16 v[114:117], v[188:191], v[198:201], v[114:117]
	v_mfma_f32_16x16x32_bf16 v[102:105], v[180:183], v[206:209], v[102:105]
	v_mfma_f32_16x16x32_bf16 v[98:101], v[188:191], v[206:209], v[98:101]
	v_mfma_f32_16x16x32_bf16 v[86:89], v[180:183], v[214:217], v[86:89]
	v_mfma_f32_16x16x32_bf16 v[82:85], v[188:191], v[214:217], v[82:85]
	v_mfma_f32_16x16x32_bf16 v[70:73], v[180:183], v[222:225], v[70:73]
	v_mfma_f32_16x16x32_bf16 v[66:69], v[188:191], v[222:225], v[66:69]
	s_barrier
; #define PG8_STAGE(bufoff, gbase, voff) do { _Pragma("unroll") for (int _i = 0; _i < 2; ++_i) \
;         __builtin_amdgcn_global_load_lds((const unsigned*)((const char*)(gbase) + (voff)[_i]), (PG8_LAS unsigned*)(lds + (bufoff) + ldsw + _i * 8192), 16, 0, 0); } while (0)
; #define PG8_LDA(dst, b, h) do { _Pragma("unroll") for (int m = 0; m < 4; ++m) _Pragma("unroll") for (int k = 0; k < 2; ++k) dst[m][k] = *(const PG8_LAS bf16x8*)(lds + PG8_SA(b, h) + aoff + m * 2048 + k * 1024); } while (0)
; #define PG8_MMA(ai, bj, At, Bt) do { __builtin_amdgcn_s_setprio(1); _Pragma("unroll") for (int m = 0; m < 4; ++m) _Pragma("unroll") for (int n = 0; n < 2; ++n) _Pragma("unroll") for (int k = 0; k < 2; ++k) \
;         acc[ai][bj][m][n] = __builtin_amdgcn_mfma_f32_16x16x32_bf16(Bt[n][k], At[m][k], acc[ai][bj][m][n], 0, 0, 0); __builtin_amdgcn_s_setprio(0); } while (0)
; #define PG8_WAIT_V(n) asm volatile("s_waitcnt vmcnt(" #n ")" ::: "memory")
; #define PG8_WAIT_L(n) asm volatile("s_waitcnt lgkmcnt(" #n ")" ::: "memory")
; #define PG8_BAR __builtin_amdgcn_s_barrier()
; #define PG8_SCHED __builtin_amdgcn_sched_barrier(0)
; template <class Epi, class Sched, bool ALIGN_EPI = false, bool SP2 = false>
; __device__ __forceinline__ void gemm_phase(PG8_LAS unsigned char* lds, const Gemm g, const Sched& S, const Epi& E) {
;     ...
;             PG8_LDA(At, 1, 1); PG8_STAGE(PG8_SB(1, 0), b3, voffB); PG8_STAGE(PG8_SB(1, 1), b3 + hstep, voffB); PG8_STAGE(PG8_SA(1, 0), a3, voffA);
;             PG8_WAIT_V(8); PG8_WAIT_L(0); PG8_BAR; PG8_MMA(1, 0, At, B0); PG8_MMA(1, 1, At, B1); PG8_BAR; PG8_SCHED;
;     ...
;         if constexpr (ALIGN_EPI) { if (wr == 0) PG8_BAR; }
	s_setprio 0
	s_add_i32 s46, s72, s51
	v_lshl_add_u64 v[226:227], v[226:227], 0, s[36:37]
	s_mov_b32 m0, s46
	ds_read_b128 v[192:195], v162 offset:49152
	ds_read_b128 v[198:201], v162 offset:50176
	ds_read_b128 v[202:205], v162 offset:51200
	ds_read_b128 v[206:209], v162 offset:52224
	ds_read_b128 v[210:213], v162 offset:53248
	ds_read_b128 v[214:217], v162 offset:54272
	ds_read_b128 v[218:221], v162 offset:55296
	ds_read_b128 v[222:225], v162 offset:56320
	global_load_lds_dwordx4 v[226:227], off
	s_add_i32 m0, s46, 0x2000
	s_add_u32 s44, s44, 0x2b0080
	v_lshl_add_u64 v[226:227], v[228:229], 0, s[36:37]
	s_addc_u32 s45, s45, 0
	s_add_i32 s46, s73, s51
	global_load_lds_dwordx4 v[226:227], off
	v_lshl_add_u64 v[226:227], s[44:45], 0, v[132:133]
	s_mov_b32 m0, s46
	s_nop 0
	global_load_lds_dwordx4 v[226:227], off
	v_lshl_add_u64 v[226:227], s[44:45], 0, v[136:137]
	s_add_i32 m0, s46, 0x2000
	s_nop 0
	global_load_lds_dwordx4 v[226:227], off
	v_lshl_add_u64 v[226:227], v[230:231], 0, s[36:37]
	s_mov_b32 m0, s57
	s_nop 0
	global_load_lds_dwordx4 v[226:227], off
	v_lshl_add_u64 v[226:227], v[232:233], 0, s[36:37]
	s_mov_b32 m0, s58
	s_nop 0
	global_load_lds_dwordx4 v[226:227], off
	s_waitcnt vmcnt(8)
	s_waitcnt lgkmcnt(0)
	s_setprio 1
	s_barrier
	v_mfma_f32_16x16x32_bf16 v[62:65], v[146:149], v[192:195], v[62:65]
	v_mfma_f32_16x16x32_bf16 v[58:61], v[168:171], v[192:195], v[58:61]
	v_mfma_f32_16x16x32_bf16 v[46:49], v[146:149], v[202:205], v[46:49]
	v_mfma_f32_16x16x32_bf16 v[42:45], v[168:171], v[202:205], v[42:45]
	v_mfma_f32_16x16x32_bf16 v[30:33], v[146:149], v[210:213], v[30:33]
	v_mfma_f32_16x16x32_bf16 v[26:29], v[168:171], v[210:213], v[26:29]
	v_mfma_f32_16x16x32_bf16 v[14:17], v[146:149], v[218:221], v[14:17]
	v_mfma_f32_16x16x32_bf16 v[10:13], v[168:171], v[218:221], v[10:13]
	v_mfma_f32_16x16x32_bf16 v[62:65], v[164:167], v[198:201], v[62:65]
	v_mfma_f32_16x16x32_bf16 v[58:61], v[172:175], v[198:201], v[58:61]
	v_mfma_f32_16x16x32_bf16 v[46:49], v[164:167], v[206:209], v[46:49]
	v_mfma_f32_16x16x32_bf16 v[42:45], v[172:175], v[206:209], v[42:45]
	v_mfma_f32_16x16x32_bf16 v[30:33], v[164:167], v[214:217], v[30:33]
	v_mfma_f32_16x16x32_bf16 v[26:29], v[172:175], v[214:217], v[26:29]
	v_mfma_f32_16x16x32_bf16 v[14:17], v[164:167], v[222:225], v[14:17]
	v_mfma_f32_16x16x32_bf16 v[10:13], v[172:175], v[222:225], v[10:13]
	s_setprio 0
	s_setprio 1
	v_mfma_f32_16x16x32_bf16 v[54:57], v[176:179], v[192:195], v[54:57]
	v_mfma_f32_16x16x32_bf16 v[50:53], v[184:187], v[192:195], v[50:53]
	v_mfma_f32_16x16x32_bf16 v[38:41], v[176:179], v[202:205], v[38:41]
	v_mfma_f32_16x16x32_bf16 v[34:37], v[184:187], v[202:205], v[34:37]
	v_mfma_f32_16x16x32_bf16 v[22:25], v[176:179], v[210:213], v[22:25]
	v_mfma_f32_16x16x32_bf16 v[18:21], v[184:187], v[210:213], v[18:21]
	v_mfma_f32_16x16x32_bf16 v[6:9], v[176:179], v[218:221], v[6:9]
	v_mfma_f32_16x16x32_bf16 v[2:5], v[184:187], v[218:221], v[2:5]
	v_mfma_f32_16x16x32_bf16 v[54:57], v[180:183], v[198:201], v[54:57]
	v_mfma_f32_16x16x32_bf16 v[50:53], v[188:191], v[198:201], v[50:53]
	v_mfma_f32_16x16x32_bf16 v[38:41], v[180:183], v[206:209], v[38:41]
	v_mfma_f32_16x16x32_bf16 v[34:37], v[188:191], v[206:209], v[34:37]
	v_mfma_f32_16x16x32_bf16 v[22:25], v[180:183], v[214:217], v[22:25]
	v_mfma_f32_16x16x32_bf16 v[18:21], v[188:191], v[214:217], v[18:21]
	v_mfma_f32_16x16x32_bf16 v[6:9], v[180:183], v[222:225], v[6:9]
	v_mfma_f32_16x16x32_bf16 v[2:5], v[188:191], v[222:225], v[2:5]
	s_barrier
	s_setprio 0
	s_add_i32 s71, s71, 2
	s_add_u32 s42, s42, 0x100
	s_addc_u32 s43, s43, 0
	s_add_u32 s69, s69, 0x100
	s_addc_u32 s70, s70, 0
	s_cmpk_gt_u32 s71, 0xa9
	s_cbranch_scc0 .LBB0_984
	s_and_b64 vcc, exec, s[38:39]
	s_cbranch_vccz .LBB0_987
	s_barrier
